# speedup vs baseline: 1.0083x; 1.0083x over previous
; template <int D, int ROT0, int HALF, bool GAIN, bool KEEP = true>
; DI void chunk_nr(u16* p, const float* __restrict__ gain, const float* __restrict__ tab) {
;     ...
;   if (GAIN) {
;     float ss = 0.f;
; #pragma unroll
;     for (int v = 0; v < NV; ++v) {
;       const f32x8 f = bf8_to_f32(RAWV(v));
; #pragma unroll
;       for (int e = 0; e < 8; ++e) ss += f[e] * f[e];
;       if (!KEEP && (v & 7) == 7) __builtin_amdgcn_sched_barrier(0);
;     }
; DI void postproc2_phase(const Params& p, int layer) {
;     ...
;       u16* kp = p.MLAK + (long)tok * 768 + (slot - 4) * 192;
;       const u16* kr = p.PROJ + (long)tok * PW + BKR;
; #pragma unroll
;       for (int v = 0; v < 8; ++v) *(u32x4*)(kp + 128 + v * 8) = *(const u32x4*)(kr + v * 8);
;       chunk_nr<192, 128, 32, true, false>(kp, p.mla_qk_norm + layer * 384 + 192, tb);
.LBB0_191:
	v_ashrrev_i32_e32 v0, 31, v27
	v_lshrrev_b32_e32 v0, 18, v0
	v_lshl_add_u64 v[2:3], v[26:27], 0, v[0:1]
	v_and_b32_e32 v0, 0xffffc000, v2
	v_sub_co_u32_e32 v0, vcc, v26, v0
	v_readfirstlane_b32 s9, v27
	v_ashrrev_i16_e32 v2, 15, v0
	s_ashr_i32 s10, s9, 31
	v_lshrrev_b16_e32 v2, 4, v2
	v_readfirstlane_b32 s8, v26
	s_lshr_b32 s10, s10, 18
	v_add_u16_e32 v2, v0, v2
	s_add_u32 s10, s8, s10
	v_and_b32_e32 v2, 0xfffff000, v2
	s_addc_u32 s11, s9, 0
	v_sub_u16_e32 v2, v0, v2
	s_ashr_i64 s[12:13], s[10:11], 14
	v_mul_hi_i32_i24_sdwa v3, sext(v2), s59 dst_sel:DWORD dst_unused:UNUSED_PAD src0_sel:WORD_0 src1_sel:DWORD
	v_mul_i32_i24_sdwa v2, sext(v2), s59 dst_sel:DWORD dst_unused:UNUSED_PAD src0_sel:WORD_0 src1_sel:DWORD
	v_cmp_gt_i64_e32 vcc, s[8:9], v[192:193]
	v_lshl_add_u64 v[28:29], s[44:45], 0, v[2:3]
	v_mul_hi_i32_i24_e32 v31, 0x600, v0
	v_mul_i32_i24_e32 v30, 0x600, v0
	s_mov_b64 s[10:11], -1
	s_mul_i32 s9, s12, 0xc0
	s_cbranch_vccz .LBB0_193
	v_readlane_b32 s12, v249, 6
	v_readlane_b32 s10, v249, 29
	v_readlane_b32 s14, v249, 8
	v_readlane_b32 s15, v249, 9
	v_readlane_b32 s18, v249, 12
	v_readlane_b32 s19, v249, 13
	v_readlane_b32 s11, v249, 30
	s_mov_b32 s15, s11
	v_lshl_add_u64 v[2:3], s[18:19], 0, v[30:31]
	s_add_i32 s14, s9, 0xfffffd00
	v_readlane_b32 s13, v249, 7
	v_lshl_add_u64 v[32:33], s[14:15], 1, v[2:3]
	v_mul_hi_i32_i24_e32 v3, 0x2600, v0
	v_mul_i32_i24_e32 v2, 0x2600, v0
	v_lshl_add_u64 v[2:3], s[12:13], 0, v[2:3]
	s_waitcnt vmcnt(0)
	v_add_co_u32_e32 v6, vcc, 0x2000, v2
	v_readlane_b32 s16, v249, 10
	s_nop 0
	v_addc_co_u32_e32 v7, vcc, 0, v3, vcc
	global_load_dwordx4 v[8:11], v[6:7], off offset:1152
	global_load_dwordx4 v[12:15], v[6:7], off offset:1168
	global_load_dwordx4 v[16:19], v[6:7], off offset:1184
	global_load_dwordx4 v[20:23], v[6:7], off offset:1200
	global_load_dwordx4 v[36:39], v[6:7], off offset:1216
	global_load_dwordx4 v[40:43], v[6:7], off offset:1232
	global_load_dwordx4 v[44:47], v[6:7], off offset:1248
	global_load_dwordx4 v[48:51], v[6:7], off offset:1264
	v_readlane_b32 s17, v249, 11
	v_writelane_b32 v249, s10, 29
	v_writelane_b32 v249, s11, 30
	s_waitcnt vmcnt(0)
	global_store_dwordx4 v[32:33], v[8:11], off offset:256
	global_store_dwordx4 v[32:33], v[12:15], off offset:272
	global_store_dwordx4 v[32:33], v[16:19], off offset:288
	global_store_dwordx4 v[32:33], v[20:23], off offset:304
	global_store_dwordx4 v[32:33], v[36:39], off offset:320
	global_store_dwordx4 v[32:33], v[40:43], off offset:336
	global_store_dwordx4 v[32:33], v[44:47], off offset:352
	global_store_dwordx4 v[32:33], v[48:51], off offset:368
	global_load_dwordx4 v[2:5], v[32:33], off offset:48
	s_nop 0
	global_load_dwordx4 v[6:9], v[32:33], off offset:32
	global_load_dwordx4 v[10:13], v[32:33], off offset:16
	global_load_dwordx4 v[14:17], v[32:33], off
	s_waitcnt vmcnt(0)
	v_and_b32_e32 v0, 0xffff0000, v14
	v_lshlrev_b32_e32 v18, 16, v14
	v_mul_f32_e32 v0, v0, v0
	v_lshlrev_b32_e32 v14, 16, v15
	v_fmac_f32_e32 v0, v18, v18
	v_and_b32_e32 v15, 0xffff0000, v15
	v_fmac_f32_e32 v0, v14, v14
	v_lshlrev_b32_e32 v19, 16, v16
	v_fmac_f32_e32 v0, v15, v15
	v_and_b32_e32 v16, 0xffff0000, v16
	v_fmac_f32_e32 v0, v19, v19
	v_lshlrev_b32_e32 v20, 16, v17
	v_fmac_f32_e32 v0, v16, v16
	v_and_b32_e32 v17, 0xffff0000, v17
	v_fmac_f32_e32 v0, v20, v20
	v_fmac_f32_e32 v0, v17, v17
	v_lshlrev_b32_e32 v14, 16, v10
	v_and_b32_e32 v10, 0xffff0000, v10
	v_fmac_f32_e32 v0, v14, v14
	v_lshlrev_b32_e32 v15, 16, v11
	v_fmac_f32_e32 v0, v10, v10
	v_and_b32_e32 v11, 0xffff0000, v11
	v_fmac_f32_e32 v0, v15, v15
	v_lshlrev_b32_e32 v16, 16, v12
	v_fmac_f32_e32 v0, v11, v11
	v_and_b32_e32 v12, 0xffff0000, v12
	v_fmac_f32_e32 v0, v16, v16
	v_lshlrev_b32_e32 v17, 16, v13
	v_fmac_f32_e32 v0, v12, v12
	v_and_b32_e32 v13, 0xffff0000, v13
	v_fmac_f32_e32 v0, v17, v17
	v_fmac_f32_e32 v0, v13, v13
	v_lshlrev_b32_e32 v10, 16, v6
	v_and_b32_e32 v6, 0xffff0000, v6
	v_fmac_f32_e32 v0, v10, v10
	v_lshlrev_b32_e32 v11, 16, v7
	v_fmac_f32_e32 v0, v6, v6
	v_and_b32_e32 v7, 0xffff0000, v7
	v_fmac_f32_e32 v0, v11, v11
	v_lshlrev_b32_e32 v12, 16, v8
	v_fmac_f32_e32 v0, v7, v7
	v_and_b32_e32 v8, 0xffff0000, v8
	v_fmac_f32_e32 v0, v12, v12
	v_lshlrev_b32_e32 v13, 16, v9
	v_fmac_f32_e32 v0, v8, v8
	v_and_b32_e32 v9, 0xffff0000, v9
	v_fmac_f32_e32 v0, v13, v13
	v_fmac_f32_e32 v0, v9, v9
	v_lshlrev_b32_e32 v6, 16, v2
	v_and_b32_e32 v2, 0xffff0000, v2
	v_fmac_f32_e32 v0, v6, v6
	v_lshlrev_b32_e32 v7, 16, v3
	v_fmac_f32_e32 v0, v2, v2
	v_and_b32_e32 v3, 0xffff0000, v3
	v_fmac_f32_e32 v0, v7, v7
	v_lshlrev_b32_e32 v8, 16, v4
	v_fmac_f32_e32 v0, v3, v3
	v_and_b32_e32 v4, 0xffff0000, v4
	v_fmac_f32_e32 v0, v8, v8
	v_lshlrev_b32_e32 v9, 16, v5
	v_fmac_f32_e32 v0, v4, v4
	v_and_b32_e32 v5, 0xffff0000, v5
	v_fmac_f32_e32 v0, v9, v9
	v_fmac_f32_e32 v0, v5, v5
	global_load_dwordx4 v[2:5], v[32:33], off offset:112
	global_load_dwordx4 v[6:9], v[32:33], off offset:96
	global_load_dwordx4 v[10:13], v[32:33], off offset:80
	global_load_dwordx4 v[14:17], v[32:33], off offset:64
	s_waitcnt vmcnt(0)
; template <int D, int ROT0, int HALF, bool GAIN, bool KEEP = true>
; DI void chunk_nr(u16* p, const float* __restrict__ gain, const float* __restrict__ tab) {
;     ...
;   if (GAIN) {
;     float ss = 0.f;
; #pragma unroll
;     for (int v = 0; v < NV; ++v) {
;       const f32x8 f = bf8_to_f32(RAWV(v));
; #pragma unroll
;       for (int e = 0; e < 8; ++e) ss += f[e] * f[e];
;       if (!KEEP && (v & 7) == 7) __builtin_amdgcn_sched_barrier(0);
;     }
	v_lshlrev_b32_e32 v18, 16, v14
	v_and_b32_e32 v14, 0xffff0000, v14
	v_fmac_f32_e32 v0, v18, v18
	v_lshlrev_b32_e32 v19, 16, v15
	v_fmac_f32_e32 v0, v14, v14
	v_and_b32_e32 v15, 0xffff0000, v15
	v_fmac_f32_e32 v0, v19, v19
	v_lshlrev_b32_e32 v20, 16, v16
	v_fmac_f32_e32 v0, v15, v15
	v_and_b32_e32 v16, 0xffff0000, v16
	v_fmac_f32_e32 v0, v20, v20
	v_lshlrev_b32_e32 v21, 16, v17
	v_fmac_f32_e32 v0, v16, v16
	v_and_b32_e32 v17, 0xffff0000, v17
	v_fmac_f32_e32 v0, v21, v21
	v_fmac_f32_e32 v0, v17, v17
	v_lshlrev_b32_e32 v14, 16, v10
	v_and_b32_e32 v10, 0xffff0000, v10
	v_fmac_f32_e32 v0, v14, v14
	v_lshlrev_b32_e32 v15, 16, v11
	v_fmac_f32_e32 v0, v10, v10
	v_and_b32_e32 v11, 0xffff0000, v11
	v_fmac_f32_e32 v0, v15, v15
	v_lshlrev_b32_e32 v16, 16, v12
	v_fmac_f32_e32 v0, v11, v11
	v_and_b32_e32 v12, 0xffff0000, v12
	v_fmac_f32_e32 v0, v16, v16
	v_lshlrev_b32_e32 v17, 16, v13
	v_fmac_f32_e32 v0, v12, v12
	v_and_b32_e32 v13, 0xffff0000, v13
	v_fmac_f32_e32 v0, v17, v17
	v_fmac_f32_e32 v0, v13, v13
	v_lshlrev_b32_e32 v10, 16, v6
	v_and_b32_e32 v6, 0xffff0000, v6
	v_fmac_f32_e32 v0, v10, v10
	v_lshlrev_b32_e32 v11, 16, v7
	v_fmac_f32_e32 v0, v6, v6
	v_and_b32_e32 v7, 0xffff0000, v7
	v_fmac_f32_e32 v0, v11, v11
	v_lshlrev_b32_e32 v12, 16, v8
	v_fmac_f32_e32 v0, v7, v7
	v_and_b32_e32 v8, 0xffff0000, v8
	v_fmac_f32_e32 v0, v12, v12
	v_lshlrev_b32_e32 v13, 16, v9
	v_fmac_f32_e32 v0, v8, v8
	v_and_b32_e32 v9, 0xffff0000, v9
	v_fmac_f32_e32 v0, v13, v13
	v_fmac_f32_e32 v0, v9, v9
	v_lshlrev_b32_e32 v6, 16, v2
	v_and_b32_e32 v2, 0xffff0000, v2
	v_fmac_f32_e32 v0, v6, v6
	v_lshlrev_b32_e32 v7, 16, v3
	v_fmac_f32_e32 v0, v2, v2
	v_and_b32_e32 v3, 0xffff0000, v3
	v_fmac_f32_e32 v0, v7, v7
	v_lshlrev_b32_e32 v8, 16, v4
	v_fmac_f32_e32 v0, v3, v3
	v_and_b32_e32 v4, 0xffff0000, v4
	v_fmac_f32_e32 v0, v8, v8
	v_lshlrev_b32_e32 v9, 16, v5
	v_fmac_f32_e32 v0, v4, v4
	v_and_b32_e32 v5, 0xffff0000, v5
	v_fmac_f32_e32 v0, v9, v9
	v_fmac_f32_e32 v0, v5, v5
	global_load_dwordx4 v[2:5], v[32:33], off offset:176
	global_load_dwordx4 v[6:9], v[32:33], off offset:160
	global_load_dwordx4 v[10:13], v[32:33], off offset:144
	global_load_dwordx4 v[14:17], v[32:33], off offset:128
	s_waitcnt vmcnt(0)
	v_lshlrev_b32_e32 v18, 16, v14
	v_and_b32_e32 v14, 0xffff0000, v14
	v_fmac_f32_e32 v0, v18, v18
	v_lshlrev_b32_e32 v19, 16, v15
	v_fmac_f32_e32 v0, v14, v14
	v_and_b32_e32 v15, 0xffff0000, v15
	v_fmac_f32_e32 v0, v19, v19
	v_lshlrev_b32_e32 v20, 16, v16
	v_fmac_f32_e32 v0, v15, v15
	v_and_b32_e32 v16, 0xffff0000, v16
	v_fmac_f32_e32 v0, v20, v20
	v_lshlrev_b32_e32 v21, 16, v17
	v_fmac_f32_e32 v0, v16, v16
	v_and_b32_e32 v17, 0xffff0000, v17
	v_fmac_f32_e32 v0, v21, v21
	v_fmac_f32_e32 v0, v17, v17
	v_lshlrev_b32_e32 v14, 16, v10
	v_and_b32_e32 v10, 0xffff0000, v10
	v_fmac_f32_e32 v0, v14, v14
	v_lshlrev_b32_e32 v15, 16, v11
	v_fmac_f32_e32 v0, v10, v10
	v_and_b32_e32 v11, 0xffff0000, v11
	v_fmac_f32_e32 v0, v15, v15
	v_lshlrev_b32_e32 v16, 16, v12
	v_fmac_f32_e32 v0, v11, v11
	v_and_b32_e32 v12, 0xffff0000, v12
	v_fmac_f32_e32 v0, v16, v16
	v_lshlrev_b32_e32 v17, 16, v13
	v_fmac_f32_e32 v0, v12, v12
	v_and_b32_e32 v13, 0xffff0000, v13
	v_fmac_f32_e32 v0, v17, v17
	v_fmac_f32_e32 v0, v13, v13
	v_lshlrev_b32_e32 v10, 16, v6
	v_and_b32_e32 v6, 0xffff0000, v6
	v_fmac_f32_e32 v0, v10, v10
	v_lshlrev_b32_e32 v11, 16, v7
	v_fmac_f32_e32 v0, v6, v6
	v_and_b32_e32 v7, 0xffff0000, v7
	v_fmac_f32_e32 v0, v11, v11
	v_lshlrev_b32_e32 v12, 16, v8
	v_fmac_f32_e32 v0, v7, v7
	v_and_b32_e32 v8, 0xffff0000, v8
	v_fmac_f32_e32 v0, v12, v12
	v_lshlrev_b32_e32 v13, 16, v9
	v_fmac_f32_e32 v0, v8, v8
	v_and_b32_e32 v9, 0xffff0000, v9
	v_fmac_f32_e32 v0, v13, v13
	v_fmac_f32_e32 v0, v9, v9
	v_lshlrev_b32_e32 v6, 16, v2
	v_and_b32_e32 v2, 0xffff0000, v2
	v_fmac_f32_e32 v0, v6, v6
	v_lshlrev_b32_e32 v7, 16, v3
	v_fmac_f32_e32 v0, v2, v2
	v_and_b32_e32 v3, 0xffff0000, v3
	v_fmac_f32_e32 v0, v7, v7
	v_lshlrev_b32_e32 v8, 16, v4
	v_fmac_f32_e32 v0, v3, v3
	v_and_b32_e32 v4, 0xffff0000, v4
	v_fmac_f32_e32 v0, v8, v8
	v_lshlrev_b32_e32 v9, 16, v5
	v_fmac_f32_e32 v0, v4, v4
	v_and_b32_e32 v5, 0xffff0000, v5
	v_fmac_f32_e32 v0, v9, v9
	v_fmac_f32_e32 v0, v5, v5
	global_load_dwordx4 v[2:5], v[32:33], off offset:240
	global_load_dwordx4 v[6:9], v[32:33], off offset:224
	global_load_dwordx4 v[10:13], v[32:33], off offset:208
	global_load_dwordx4 v[14:17], v[32:33], off offset:192
	s_waitcnt vmcnt(0)
	v_lshlrev_b32_e32 v18, 16, v14
	v_and_b32_e32 v14, 0xffff0000, v14
	v_fmac_f32_e32 v0, v18, v18
	v_lshlrev_b32_e32 v19, 16, v15
	v_fmac_f32_e32 v0, v14, v14
	v_and_b32_e32 v15, 0xffff0000, v15
	v_fmac_f32_e32 v0, v19, v19
	v_lshlrev_b32_e32 v20, 16, v16
	v_fmac_f32_e32 v0, v15, v15
	v_and_b32_e32 v16, 0xffff0000, v16
	v_fmac_f32_e32 v0, v20, v20
	v_lshlrev_b32_e32 v21, 16, v17
	v_fmac_f32_e32 v0, v16, v16
	v_and_b32_e32 v17, 0xffff0000, v17
	v_fmac_f32_e32 v0, v21, v21
	v_fmac_f32_e32 v0, v17, v17
	v_lshlrev_b32_e32 v14, 16, v10
	v_and_b32_e32 v10, 0xffff0000, v10
	v_fmac_f32_e32 v0, v14, v14
	v_lshlrev_b32_e32 v15, 16, v11
	v_fmac_f32_e32 v0, v10, v10
	v_and_b32_e32 v11, 0xffff0000, v11
	v_fmac_f32_e32 v0, v15, v15
	v_lshlrev_b32_e32 v16, 16, v12
	v_fmac_f32_e32 v0, v11, v11
	v_and_b32_e32 v12, 0xffff0000, v12
	v_fmac_f32_e32 v0, v16, v16
	v_lshlrev_b32_e32 v17, 16, v13
	v_fmac_f32_e32 v0, v12, v12
	v_and_b32_e32 v13, 0xffff0000, v13
	v_fmac_f32_e32 v0, v17, v17
	v_fmac_f32_e32 v0, v13, v13
	v_lshlrev_b32_e32 v10, 16, v6
	v_and_b32_e32 v6, 0xffff0000, v6
	v_fmac_f32_e32 v0, v10, v10
	v_lshlrev_b32_e32 v11, 16, v7
	v_fmac_f32_e32 v0, v6, v6
	v_and_b32_e32 v7, 0xffff0000, v7
	v_fmac_f32_e32 v0, v11, v11
	v_lshlrev_b32_e32 v12, 16, v8
	v_fmac_f32_e32 v0, v7, v7
	v_and_b32_e32 v8, 0xffff0000, v8
	v_fmac_f32_e32 v0, v12, v12
	v_lshlrev_b32_e32 v13, 16, v9
	v_fmac_f32_e32 v0, v8, v8
	v_and_b32_e32 v9, 0xffff0000, v9
	v_fmac_f32_e32 v0, v13, v13
	v_fmac_f32_e32 v0, v9, v9
	v_lshlrev_b32_e32 v6, 16, v2
	v_and_b32_e32 v2, 0xffff0000, v2
	v_fmac_f32_e32 v0, v6, v6
	v_lshlrev_b32_e32 v7, 16, v3
	v_fmac_f32_e32 v0, v2, v2
	v_and_b32_e32 v3, 0xffff0000, v3
	v_fmac_f32_e32 v0, v7, v7
	v_lshlrev_b32_e32 v8, 16, v4
	v_fmac_f32_e32 v0, v3, v3
	v_and_b32_e32 v4, 0xffff0000, v4
	v_fmac_f32_e32 v0, v8, v8
	v_lshlrev_b32_e32 v9, 16, v5
	v_fmac_f32_e32 v0, v4, v4
	v_and_b32_e32 v5, 0xffff0000, v5
	v_fmac_f32_e32 v0, v9, v9
	v_fmac_f32_e32 v0, v5, v5
	global_load_dwordx4 v[2:5], v[32:33], off offset:304
	global_load_dwordx4 v[6:9], v[32:33], off offset:288
	global_load_dwordx4 v[10:13], v[32:33], off offset:272
	global_load_dwordx4 v[14:17], v[32:33], off offset:256
	s_waitcnt vmcnt(0)
; template <int D, int ROT0, int HALF, bool GAIN, bool KEEP = true>
; DI void chunk_nr(u16* p, const float* __restrict__ gain, const float* __restrict__ tab) {
;     ...
;   if (GAIN) {
;     float ss = 0.f;
; #pragma unroll
;     for (int v = 0; v < NV; ++v) {
;       const f32x8 f = bf8_to_f32(RAWV(v));
; #pragma unroll
;       for (int e = 0; e < 8; ++e) ss += f[e] * f[e];
;       if (!KEEP && (v & 7) == 7) __builtin_amdgcn_sched_barrier(0);
;     }
;     rstd = rsqrtf(ss * (1.0f / D) + EPS);
;     ...
;     } else if (GAIN) {
;       f32x8 x1 = bf8_to_f32(RAWV(v));
;       const f32x8 g1 = *(const f32x8*)(gain + v * 8);
; #pragma unroll
;       for (int e = 0; e < 8; ++e) x1[e] = x1[e] * rstd * g1[e];
;       *(u32x4*)(p + v * 8) = f32_to_bf8(x1);
	v_lshlrev_b32_e32 v18, 16, v14
	v_and_b32_e32 v14, 0xffff0000, v14
	v_fmac_f32_e32 v0, v18, v18
	v_lshlrev_b32_e32 v19, 16, v15
	v_fmac_f32_e32 v0, v14, v14
	v_and_b32_e32 v15, 0xffff0000, v15
	v_fmac_f32_e32 v0, v19, v19
	v_lshlrev_b32_e32 v20, 16, v16
	v_fmac_f32_e32 v0, v15, v15
	v_and_b32_e32 v16, 0xffff0000, v16
	v_fmac_f32_e32 v0, v20, v20
	v_lshlrev_b32_e32 v21, 16, v17
	v_fmac_f32_e32 v0, v16, v16
	v_and_b32_e32 v17, 0xffff0000, v17
	v_fmac_f32_e32 v0, v21, v21
	v_fmac_f32_e32 v0, v17, v17
	v_lshlrev_b32_e32 v14, 16, v10
	v_and_b32_e32 v10, 0xffff0000, v10
	v_fmac_f32_e32 v0, v14, v14
	v_lshlrev_b32_e32 v15, 16, v11
	v_fmac_f32_e32 v0, v10, v10
	v_and_b32_e32 v11, 0xffff0000, v11
	v_fmac_f32_e32 v0, v15, v15
	v_lshlrev_b32_e32 v16, 16, v12
	v_fmac_f32_e32 v0, v11, v11
	v_and_b32_e32 v12, 0xffff0000, v12
	v_fmac_f32_e32 v0, v16, v16
	v_lshlrev_b32_e32 v17, 16, v13
	v_fmac_f32_e32 v0, v12, v12
	v_and_b32_e32 v13, 0xffff0000, v13
	v_fmac_f32_e32 v0, v17, v17
	v_fmac_f32_e32 v0, v13, v13
	v_lshlrev_b32_e32 v10, 16, v6
	v_and_b32_e32 v6, 0xffff0000, v6
	v_fmac_f32_e32 v0, v10, v10
	v_lshlrev_b32_e32 v11, 16, v7
	v_fmac_f32_e32 v0, v6, v6
	v_and_b32_e32 v7, 0xffff0000, v7
	v_fmac_f32_e32 v0, v11, v11
	v_lshlrev_b32_e32 v12, 16, v8
	v_fmac_f32_e32 v0, v7, v7
	v_and_b32_e32 v8, 0xffff0000, v8
	v_fmac_f32_e32 v0, v12, v12
	v_lshlrev_b32_e32 v13, 16, v9
	v_fmac_f32_e32 v0, v8, v8
	v_and_b32_e32 v9, 0xffff0000, v9
	v_fmac_f32_e32 v0, v13, v13
	v_fmac_f32_e32 v0, v9, v9
	v_lshlrev_b32_e32 v6, 16, v2
	v_and_b32_e32 v2, 0xffff0000, v2
	v_fmac_f32_e32 v0, v6, v6
	v_lshlrev_b32_e32 v7, 16, v3
	v_fmac_f32_e32 v0, v2, v2
	v_and_b32_e32 v3, 0xffff0000, v3
	v_fmac_f32_e32 v0, v7, v7
	v_lshlrev_b32_e32 v8, 16, v4
	v_fmac_f32_e32 v0, v3, v3
	v_and_b32_e32 v4, 0xffff0000, v4
	v_fmac_f32_e32 v0, v8, v8
	v_lshlrev_b32_e32 v9, 16, v5
	v_fmac_f32_e32 v0, v4, v4
	v_and_b32_e32 v5, 0xffff0000, v5
	v_fmac_f32_e32 v0, v9, v9
	v_fmac_f32_e32 v0, v5, v5
	global_load_dwordx4 v[2:5], v[32:33], off offset:368
	global_load_dwordx4 v[6:9], v[32:33], off offset:352
	global_load_dwordx4 v[10:13], v[32:33], off offset:336
	global_load_dwordx4 v[14:17], v[32:33], off offset:320
	s_waitcnt vmcnt(0)
	v_lshlrev_b32_e32 v18, 16, v14
	v_and_b32_e32 v14, 0xffff0000, v14
	v_fmac_f32_e32 v0, v18, v18
	v_lshlrev_b32_e32 v19, 16, v15
	v_fmac_f32_e32 v0, v14, v14
	v_and_b32_e32 v15, 0xffff0000, v15
	v_fmac_f32_e32 v0, v19, v19
	v_lshlrev_b32_e32 v20, 16, v16
	v_fmac_f32_e32 v0, v15, v15
	v_and_b32_e32 v16, 0xffff0000, v16
	v_fmac_f32_e32 v0, v20, v20
	v_lshlrev_b32_e32 v21, 16, v17
	v_fmac_f32_e32 v0, v16, v16
	v_and_b32_e32 v17, 0xffff0000, v17
	v_fmac_f32_e32 v0, v21, v21
	v_fmac_f32_e32 v0, v17, v17
	v_lshlrev_b32_e32 v14, 16, v10
	v_and_b32_e32 v10, 0xffff0000, v10
	v_fmac_f32_e32 v0, v14, v14
	v_lshlrev_b32_e32 v15, 16, v11
	v_fmac_f32_e32 v0, v10, v10
	v_and_b32_e32 v11, 0xffff0000, v11
	v_fmac_f32_e32 v0, v15, v15
	v_lshlrev_b32_e32 v16, 16, v12
	v_fmac_f32_e32 v0, v11, v11
	v_and_b32_e32 v12, 0xffff0000, v12
	v_fmac_f32_e32 v0, v16, v16
	v_lshlrev_b32_e32 v17, 16, v13
	v_fmac_f32_e32 v0, v12, v12
	v_and_b32_e32 v13, 0xffff0000, v13
	v_fmac_f32_e32 v0, v17, v17
	v_fmac_f32_e32 v0, v13, v13
	v_lshlrev_b32_e32 v10, 16, v6
	v_and_b32_e32 v6, 0xffff0000, v6
	v_fmac_f32_e32 v0, v10, v10
	v_lshlrev_b32_e32 v11, 16, v7
	v_fmac_f32_e32 v0, v6, v6
	v_and_b32_e32 v7, 0xffff0000, v7
	v_fmac_f32_e32 v0, v11, v11
	v_lshlrev_b32_e32 v12, 16, v8
	v_fmac_f32_e32 v0, v7, v7
	v_and_b32_e32 v8, 0xffff0000, v8
	v_fmac_f32_e32 v0, v12, v12
	v_and_b32_e32 v6, 0xffff0000, v9
	v_lshlrev_b32_e32 v7, 16, v9
	v_fmac_f32_e32 v0, v8, v8
	v_pk_mul_f32 v[6:7], v[6:7], v[6:7]
	s_nop 0
	v_add_f32_e32 v0, v7, v0
	v_add_f32_e32 v0, v6, v0
	v_and_b32_e32 v6, 0xffff0000, v2
	v_lshlrev_b32_e32 v7, 16, v2
	v_pk_mul_f32 v[6:7], v[6:7], v[6:7]
	v_and_b32_e32 v2, 0xffff0000, v3
	v_add_f32_e32 v0, v7, v0
	v_lshlrev_b32_e32 v3, 16, v3
	v_add_f32_e32 v0, v6, v0
	v_pk_mul_f32 v[2:3], v[2:3], v[2:3]
	s_nop 0
	v_add_f32_e32 v0, v3, v0
	v_add_f32_e32 v0, v2, v0
	v_and_b32_e32 v2, 0xffff0000, v4
	v_lshlrev_b32_e32 v3, 16, v4
	v_pk_mul_f32 v[2:3], v[2:3], v[2:3]
	s_nop 0
	v_add_f32_e32 v0, v3, v0
	v_add_f32_e32 v0, v2, v0
	v_and_b32_e32 v2, 0xffff0000, v5
	v_lshlrev_b32_e32 v3, 16, v5
	v_pk_mul_f32 v[2:3], v[2:3], v[2:3]
	s_nop 0
	v_add_f32_e32 v0, v3, v0
	v_add_f32_e32 v0, v2, v0
	v_fmamk_f32 v0, v0, 0x3baaaaab, v189
	v_cmp_gt_f32_e32 vcc, s55, v0
	v_mul_f32_e32 v2, 0x4b800000, v0
	s_nop 0
	v_cndmask_b32_e32 v0, v0, v2, vcc
	v_rsq_f32_e32 v0, v0
	s_nop 0
	v_mul_f32_e32 v2, 0x45800000, v0
	v_cndmask_b32_e32 v0, v0, v2, vcc
	global_load_dwordx4 v[2:5], v[32:33], off offset:48
	global_load_dwordx4 v[6:9], v[32:33], off offset:32
	global_load_dwordx4 v[14:17], v[32:33], off offset:16
	global_load_dwordx4 v[22:25], v[32:33], off
	global_load_dwordx4 v[10:13], v1, s[4:5] offset:816
	global_load_dwordx4 v[18:21], v1, s[4:5] offset:800
	global_load_dwordx4 v[34:37], v1, s[4:5] offset:784
	global_load_dwordx4 v[38:41], v1, s[4:5] offset:768
	s_waitcnt vmcnt(0)
; template <int D, int ROT0, int HALF, bool GAIN, bool KEEP = true>
; DI void chunk_nr(u16* p, const float* __restrict__ gain, const float* __restrict__ tab) {
;     ...
;     } else if (GAIN) {
;       f32x8 x1 = bf8_to_f32(RAWV(v));
;       const f32x8 g1 = *(const f32x8*)(gain + v * 8);
; #pragma unroll
;       for (int e = 0; e < 8; ++e) x1[e] = x1[e] * rstd * g1[e];
;       *(u32x4*)(p + v * 8) = f32_to_bf8(x1);
;     }
	v_lshlrev_b32_e32 v43, 16, v23
	v_lshlrev_b32_e32 v42, 16, v22
	v_and_b32_e32 v23, 0xffff0000, v23
	v_and_b32_e32 v22, 0xffff0000, v22
	v_mov_b32_e32 v44, v38
	v_mov_b32_e32 v45, v40
	v_pk_mul_f32 v[22:23], v[0:1], v[22:23] op_sel_hi:[0,1]
	v_mov_b32_e32 v40, v39
	v_lshlrev_b32_e32 v39, 16, v25
	v_lshlrev_b32_e32 v38, 16, v24
	v_and_b32_e32 v25, 0xffff0000, v25
	v_and_b32_e32 v24, 0xffff0000, v24
	v_pk_mul_f32 v[22:23], v[40:41], v[22:23]
	v_mov_b32_e32 v41, v36
	v_pk_mul_f32 v[24:25], v[0:1], v[24:25] op_sel_hi:[0,1]
	v_mov_b32_e32 v36, v35
	v_pk_mul_f32 v[42:43], v[0:1], v[42:43] op_sel_hi:[0,1]
	v_pk_mul_f32 v[38:39], v[0:1], v[38:39] op_sel_hi:[0,1]
	v_mov_b32_e32 v40, v34
	v_pk_mul_f32 v[24:25], v[36:37], v[24:25]
	v_pk_mul_f32 v[42:43], v[44:45], v[42:43]
	v_pk_mul_f32 v[38:39], v[40:41], v[38:39]
	v_bfe_u32 v34, v25, 16, 1
	v_bfe_u32 v35, v24, 16, 1
	v_bfe_u32 v36, v23, 16, 1
	v_bfe_u32 v37, v22, 16, 1
	v_add3_u32 v22, v22, v37, s54
	v_add3_u32 v23, v23, v36, s54
	v_add3_u32 v24, v24, v35, s54
	v_add3_u32 v25, v25, v34, s54
	v_bfe_u32 v34, v42, 16, 1
	v_bfe_u32 v35, v43, 16, 1
	v_bfe_u32 v36, v38, 16, 1
	v_bfe_u32 v37, v39, 16, 1
	v_add3_u32 v37, v39, v37, s54
	v_add3_u32 v36, v38, v36, s54
	v_add3_u32 v35, v43, v35, s54
	v_add3_u32 v34, v42, v34, s54
	v_lshrrev_b32_e32 v34, 16, v34
	v_lshrrev_b32_e32 v35, 16, v35
	v_lshrrev_b32_e32 v36, 16, v36
	v_lshrrev_b32_e32 v37, 16, v37
	v_and_or_b32 v25, v25, s56, v37
	v_and_or_b32 v24, v24, s56, v36
	v_and_or_b32 v23, v23, s56, v35
	v_and_or_b32 v22, v22, s56, v34
	global_store_dwordx4 v[32:33], v[22:25], off
	v_lshlrev_b32_e32 v35, 16, v7
	v_lshlrev_b32_e32 v34, 16, v6
	v_lshlrev_b32_e32 v23, 16, v15
	v_lshlrev_b32_e32 v22, 16, v14
	v_and_b32_e32 v15, 0xffff0000, v15
	v_and_b32_e32 v14, 0xffff0000, v14
	v_mov_b32_e32 v24, v18
	v_mov_b32_e32 v25, v20
	v_pk_mul_f32 v[14:15], v[0:1], v[14:15] op_sel_hi:[0,1]
	v_mov_b32_e32 v20, v19
	v_lshlrev_b32_e32 v19, 16, v17
	v_lshlrev_b32_e32 v18, 16, v16
	v_and_b32_e32 v17, 0xffff0000, v17
	v_and_b32_e32 v16, 0xffff0000, v16
	v_pk_mul_f32 v[14:15], v[20:21], v[14:15]
	v_mov_b32_e32 v21, v12
	v_pk_mul_f32 v[16:17], v[0:1], v[16:17] op_sel_hi:[0,1]
	v_mov_b32_e32 v12, v11
	v_pk_mul_f32 v[22:23], v[0:1], v[22:23] op_sel_hi:[0,1]
	v_pk_mul_f32 v[18:19], v[0:1], v[18:19] op_sel_hi:[0,1]
	v_mov_b32_e32 v20, v10
	v_pk_mul_f32 v[10:11], v[12:13], v[16:17]
	v_pk_mul_f32 v[22:23], v[24:25], v[22:23]
	v_pk_mul_f32 v[18:19], v[20:21], v[18:19]
	v_bfe_u32 v12, v11, 16, 1
	v_bfe_u32 v13, v10, 16, 1
	v_bfe_u32 v16, v15, 16, 1
	v_bfe_u32 v17, v14, 16, 1
	v_add3_u32 v14, v14, v17, s54
	v_add3_u32 v15, v15, v16, s54
	v_add3_u32 v10, v10, v13, s54
	v_add3_u32 v11, v11, v12, s54
	v_bfe_u32 v12, v22, 16, 1
	v_bfe_u32 v13, v23, 16, 1
	v_bfe_u32 v16, v18, 16, 1
	v_bfe_u32 v17, v19, 16, 1
	v_add3_u32 v17, v19, v17, s54
	v_add3_u32 v16, v18, v16, s54
	v_add3_u32 v13, v23, v13, s54
	v_add3_u32 v12, v22, v12, s54
	v_lshrrev_b32_e32 v18, 16, v12
	v_lshrrev_b32_e32 v19, 16, v13
	v_lshrrev_b32_e32 v12, 16, v16
	v_lshrrev_b32_e32 v13, 16, v17
	v_and_or_b32 v13, v11, s56, v13
	v_and_or_b32 v12, v10, s56, v12
	v_and_or_b32 v11, v15, s56, v19
	v_and_or_b32 v10, v14, s56, v18
	global_store_dwordx4 v[32:33], v[10:13], off offset:16
	global_load_dwordx4 v[10:13], v1, s[4:5] offset:880
	s_nop 0
	global_load_dwordx4 v[14:17], v1, s[4:5] offset:864
	global_load_dwordx4 v[18:21], v1, s[4:5] offset:848
	global_load_dwordx4 v[22:25], v1, s[4:5] offset:832
	v_and_b32_e32 v7, 0xffff0000, v7
	v_and_b32_e32 v6, 0xffff0000, v6
	v_pk_mul_f32 v[6:7], v[0:1], v[6:7] op_sel_hi:[0,1]
	v_pk_mul_f32 v[34:35], v[0:1], v[34:35] op_sel_hi:[0,1]
	s_waitcnt vmcnt(0)
	v_mov_b32_e32 v36, v22
	v_mov_b32_e32 v37, v24
	v_mov_b32_e32 v24, v23
	v_lshlrev_b32_e32 v23, 16, v9
	v_lshlrev_b32_e32 v22, 16, v8
	v_and_b32_e32 v9, 0xffff0000, v9
	v_and_b32_e32 v8, 0xffff0000, v8
	v_pk_mul_f32 v[6:7], v[24:25], v[6:7]
	v_mov_b32_e32 v25, v20
	v_pk_mul_f32 v[8:9], v[0:1], v[8:9] op_sel_hi:[0,1]
	v_mov_b32_e32 v20, v19
	v_pk_mul_f32 v[22:23], v[0:1], v[22:23] op_sel_hi:[0,1]
	v_mov_b32_e32 v24, v18
	v_pk_mul_f32 v[8:9], v[20:21], v[8:9]
	v_pk_mul_f32 v[34:35], v[36:37], v[34:35]
	v_pk_mul_f32 v[22:23], v[24:25], v[22:23]
	v_bfe_u32 v18, v9, 16, 1
	v_bfe_u32 v19, v8, 16, 1
	v_bfe_u32 v20, v7, 16, 1
	v_bfe_u32 v21, v6, 16, 1
	v_add3_u32 v6, v6, v21, s54
	v_add3_u32 v7, v7, v20, s54
	v_add3_u32 v8, v8, v19, s54
	v_add3_u32 v9, v9, v18, s54
	v_bfe_u32 v18, v34, 16, 1
	v_bfe_u32 v19, v35, 16, 1
	v_bfe_u32 v20, v22, 16, 1
	v_bfe_u32 v21, v23, 16, 1
	v_add3_u32 v21, v23, v21, s54
	v_add3_u32 v20, v22, v20, s54
	v_add3_u32 v19, v35, v19, s54
	v_add3_u32 v18, v34, v18, s54
	v_lshrrev_b32_e32 v18, 16, v18
	v_lshrrev_b32_e32 v19, 16, v19
	v_lshrrev_b32_e32 v20, 16, v20
	v_lshrrev_b32_e32 v21, 16, v21
	v_and_or_b32 v9, v9, s56, v21
	v_and_or_b32 v8, v8, s56, v20
	v_and_or_b32 v7, v7, s56, v19
	v_and_or_b32 v6, v6, s56, v18
	global_store_dwordx4 v[32:33], v[6:9], off offset:32
	s_nop 1
	v_lshlrev_b32_e32 v7, 16, v3
	v_lshlrev_b32_e32 v6, 16, v2
	v_and_b32_e32 v9, 0xffff0000, v3
	v_and_b32_e32 v8, 0xffff0000, v2
	v_pk_mul_f32 v[2:3], v[0:1], v[6:7] op_sel_hi:[0,1]
	v_mov_b32_e32 v6, v14
	v_mov_b32_e32 v7, v16
	v_pk_mul_f32 v[2:3], v[6:7], v[2:3]
	v_pk_mul_f32 v[6:7], v[0:1], v[8:9] op_sel_hi:[0,1]
	v_lshlrev_b32_e32 v9, 16, v5
	v_lshlrev_b32_e32 v8, 16, v4
	v_and_b32_e32 v5, 0xffff0000, v5
	v_and_b32_e32 v4, 0xffff0000, v4
	v_mov_b32_e32 v16, v15
	v_mov_b32_e32 v15, v12
	v_pk_mul_f32 v[4:5], v[0:1], v[4:5] op_sel_hi:[0,1]
	v_mov_b32_e32 v12, v11
	v_pk_mul_f32 v[6:7], v[16:17], v[6:7]
	v_pk_mul_f32 v[8:9], v[0:1], v[8:9] op_sel_hi:[0,1]
	v_mov_b32_e32 v14, v10
	v_pk_mul_f32 v[4:5], v[12:13], v[4:5]
	v_pk_mul_f32 v[8:9], v[14:15], v[8:9]
	v_bfe_u32 v10, v5, 16, 1
	v_bfe_u32 v11, v4, 16, 1
	v_bfe_u32 v12, v7, 16, 1
	v_bfe_u32 v13, v6, 16, 1
	v_add3_u32 v6, v6, v13, s54
	v_add3_u32 v7, v7, v12, s54
	v_add3_u32 v4, v4, v11, s54
	v_add3_u32 v5, v5, v10, s54
	v_bfe_u32 v10, v2, 16, 1
	v_bfe_u32 v11, v3, 16, 1
	v_bfe_u32 v12, v8, 16, 1
	v_bfe_u32 v13, v9, 16, 1
	v_add3_u32 v9, v9, v13, s54
	v_add3_u32 v8, v8, v12, s54
	v_add3_u32 v3, v3, v11, s54
	v_add3_u32 v2, v2, v10, s54
	v_lshrrev_b32_e32 v2, 16, v2
	v_lshrrev_b32_e32 v3, 16, v3
	v_lshrrev_b32_e32 v8, 16, v8
	v_lshrrev_b32_e32 v9, 16, v9
	v_and_or_b32 v5, v5, s56, v9
	v_and_or_b32 v4, v4, s56, v8
	v_and_or_b32 v3, v7, s56, v3
	v_and_or_b32 v2, v6, s56, v2
	global_store_dwordx4 v[32:33], v[2:5], off offset:48
	global_load_dwordx4 v[2:5], v[32:33], off offset:112
	s_nop 0
	global_load_dwordx4 v[6:9], v[32:33], off offset:96
	global_load_dwordx4 v[14:17], v[32:33], off offset:80
	global_load_dwordx4 v[22:25], v[32:33], off offset:64
	global_load_dwordx4 v[10:13], v1, s[4:5] offset:944
	global_load_dwordx4 v[18:21], v1, s[4:5] offset:928
	global_load_dwordx4 v[34:37], v1, s[4:5] offset:912
	global_load_dwordx4 v[38:41], v1, s[4:5] offset:896
	s_waitcnt vmcnt(0)
; template <int D, int ROT0, int HALF, bool GAIN, bool KEEP = true>
; DI void chunk_nr(u16* p, const float* __restrict__ gain, const float* __restrict__ tab) {
;     ...
;     } else if (GAIN) {
;       f32x8 x1 = bf8_to_f32(RAWV(v));
;       const f32x8 g1 = *(const f32x8*)(gain + v * 8);
; #pragma unroll
;       for (int e = 0; e < 8; ++e) x1[e] = x1[e] * rstd * g1[e];
;       *(u32x4*)(p + v * 8) = f32_to_bf8(x1);
;     }
	v_lshlrev_b32_e32 v43, 16, v23
	v_lshlrev_b32_e32 v42, 16, v22
	v_and_b32_e32 v23, 0xffff0000, v23
	v_and_b32_e32 v22, 0xffff0000, v22
	v_mov_b32_e32 v44, v38
	v_mov_b32_e32 v45, v40
	v_pk_mul_f32 v[22:23], v[0:1], v[22:23] op_sel_hi:[0,1]
	v_mov_b32_e32 v40, v39
	v_lshlrev_b32_e32 v39, 16, v25
	v_lshlrev_b32_e32 v38, 16, v24
	v_and_b32_e32 v25, 0xffff0000, v25
	v_and_b32_e32 v24, 0xffff0000, v24
	v_pk_mul_f32 v[22:23], v[40:41], v[22:23]
	v_mov_b32_e32 v41, v36
	v_pk_mul_f32 v[24:25], v[0:1], v[24:25] op_sel_hi:[0,1]
	v_mov_b32_e32 v36, v35
	v_pk_mul_f32 v[42:43], v[0:1], v[42:43] op_sel_hi:[0,1]
	v_pk_mul_f32 v[38:39], v[0:1], v[38:39] op_sel_hi:[0,1]
	v_mov_b32_e32 v40, v34
	v_pk_mul_f32 v[24:25], v[36:37], v[24:25]
	v_pk_mul_f32 v[42:43], v[44:45], v[42:43]
	v_pk_mul_f32 v[38:39], v[40:41], v[38:39]
	v_bfe_u32 v34, v25, 16, 1
	v_bfe_u32 v35, v24, 16, 1
	v_bfe_u32 v36, v23, 16, 1
	v_bfe_u32 v37, v22, 16, 1
	v_add3_u32 v22, v22, v37, s54
	v_add3_u32 v23, v23, v36, s54
	v_add3_u32 v24, v24, v35, s54
	v_add3_u32 v25, v25, v34, s54
	v_bfe_u32 v34, v42, 16, 1
	v_bfe_u32 v35, v43, 16, 1
	v_bfe_u32 v36, v38, 16, 1
	v_bfe_u32 v37, v39, 16, 1
	v_add3_u32 v37, v39, v37, s54
	v_add3_u32 v36, v38, v36, s54
	v_add3_u32 v35, v43, v35, s54
	v_add3_u32 v34, v42, v34, s54
	v_lshrrev_b32_e32 v34, 16, v34
	v_lshrrev_b32_e32 v35, 16, v35
	v_lshrrev_b32_e32 v36, 16, v36
	v_lshrrev_b32_e32 v37, 16, v37
	v_and_or_b32 v25, v25, s56, v37
	v_and_or_b32 v24, v24, s56, v36
	v_and_or_b32 v23, v23, s56, v35
	v_and_or_b32 v22, v22, s56, v34
	global_store_dwordx4 v[32:33], v[22:25], off offset:64
	v_lshlrev_b32_e32 v35, 16, v7
	v_lshlrev_b32_e32 v34, 16, v6
	v_lshlrev_b32_e32 v23, 16, v15
	v_lshlrev_b32_e32 v22, 16, v14
	v_and_b32_e32 v25, 0xffff0000, v15
	v_and_b32_e32 v24, 0xffff0000, v14
	v_pk_mul_f32 v[14:15], v[0:1], v[22:23] op_sel_hi:[0,1]
	v_mov_b32_e32 v22, v18
	v_mov_b32_e32 v23, v20
	v_pk_mul_f32 v[14:15], v[22:23], v[14:15]
	v_pk_mul_f32 v[22:23], v[0:1], v[24:25] op_sel_hi:[0,1]
	v_mov_b32_e32 v20, v19
	v_pk_mul_f32 v[18:19], v[20:21], v[22:23]
	v_lshlrev_b32_e32 v21, 16, v17
	v_lshlrev_b32_e32 v20, 16, v16
	v_and_b32_e32 v17, 0xffff0000, v17
	v_and_b32_e32 v16, 0xffff0000, v16
	v_mov_b32_e32 v23, v12
	v_pk_mul_f32 v[16:17], v[0:1], v[16:17] op_sel_hi:[0,1]
	v_mov_b32_e32 v12, v11
	v_pk_mul_f32 v[20:21], v[0:1], v[20:21] op_sel_hi:[0,1]
	v_mov_b32_e32 v22, v10
	v_pk_mul_f32 v[10:11], v[12:13], v[16:17]
	v_pk_mul_f32 v[20:21], v[22:23], v[20:21]
	v_bfe_u32 v12, v11, 16, 1
	v_bfe_u32 v13, v10, 16, 1
	v_bfe_u32 v16, v19, 16, 1
	v_bfe_u32 v17, v18, 16, 1
	v_add3_u32 v17, v18, v17, s54
	v_add3_u32 v16, v19, v16, s54
	v_add3_u32 v10, v10, v13, s54
	v_add3_u32 v11, v11, v12, s54
	v_bfe_u32 v12, v14, 16, 1
	v_bfe_u32 v13, v15, 16, 1
	v_bfe_u32 v18, v20, 16, 1
	v_bfe_u32 v19, v21, 16, 1
	v_add3_u32 v19, v21, v19, s54
	v_add3_u32 v18, v20, v18, s54
	v_add3_u32 v13, v15, v13, s54
	v_add3_u32 v12, v14, v12, s54
	v_lshrrev_b32_e32 v14, 16, v12
	v_lshrrev_b32_e32 v15, 16, v13
	v_lshrrev_b32_e32 v12, 16, v18
	v_lshrrev_b32_e32 v13, 16, v19
	v_and_or_b32 v13, v11, s56, v13
	v_and_or_b32 v12, v10, s56, v12
	v_and_or_b32 v11, v16, s56, v15
	v_and_or_b32 v10, v17, s56, v14
	global_store_dwordx4 v[32:33], v[10:13], off offset:80
	global_load_dwordx4 v[10:13], v1, s[4:5] offset:1008
	s_nop 0
	global_load_dwordx4 v[14:17], v1, s[4:5] offset:992
	global_load_dwordx4 v[18:21], v1, s[4:5] offset:976
	global_load_dwordx4 v[22:25], v1, s[4:5] offset:960
	v_and_b32_e32 v7, 0xffff0000, v7
	v_and_b32_e32 v6, 0xffff0000, v6
	v_pk_mul_f32 v[6:7], v[0:1], v[6:7] op_sel_hi:[0,1]
	v_pk_mul_f32 v[34:35], v[0:1], v[34:35] op_sel_hi:[0,1]
	s_waitcnt vmcnt(0)
	v_mov_b32_e32 v36, v22
	v_mov_b32_e32 v37, v24
	v_mov_b32_e32 v24, v23
	v_lshlrev_b32_e32 v23, 16, v9
	v_lshlrev_b32_e32 v22, 16, v8
	v_and_b32_e32 v9, 0xffff0000, v9
	v_and_b32_e32 v8, 0xffff0000, v8
	v_pk_mul_f32 v[6:7], v[24:25], v[6:7]
	v_mov_b32_e32 v25, v20
	v_pk_mul_f32 v[8:9], v[0:1], v[8:9] op_sel_hi:[0,1]
	v_mov_b32_e32 v20, v19
	v_pk_mul_f32 v[22:23], v[0:1], v[22:23] op_sel_hi:[0,1]
	v_mov_b32_e32 v24, v18
	v_pk_mul_f32 v[8:9], v[20:21], v[8:9]
	v_pk_mul_f32 v[34:35], v[36:37], v[34:35]
	v_pk_mul_f32 v[22:23], v[24:25], v[22:23]
	v_bfe_u32 v18, v9, 16, 1
	v_bfe_u32 v19, v8, 16, 1
	v_bfe_u32 v20, v7, 16, 1
	v_bfe_u32 v21, v6, 16, 1
	v_add3_u32 v6, v6, v21, s54
	v_add3_u32 v7, v7, v20, s54
	v_add3_u32 v8, v8, v19, s54
	v_add3_u32 v9, v9, v18, s54
	v_bfe_u32 v18, v34, 16, 1
	v_bfe_u32 v19, v35, 16, 1
	v_bfe_u32 v20, v22, 16, 1
	v_bfe_u32 v21, v23, 16, 1
	v_add3_u32 v21, v23, v21, s54
	v_add3_u32 v20, v22, v20, s54
	v_add3_u32 v19, v35, v19, s54
	v_add3_u32 v18, v34, v18, s54
	v_lshrrev_b32_e32 v18, 16, v18
	v_lshrrev_b32_e32 v19, 16, v19
	v_lshrrev_b32_e32 v20, 16, v20
	v_lshrrev_b32_e32 v21, 16, v21
	v_and_or_b32 v9, v9, s56, v21
	v_and_or_b32 v8, v8, s56, v20
	v_and_or_b32 v7, v7, s56, v19
	v_and_or_b32 v6, v6, s56, v18
	global_store_dwordx4 v[32:33], v[6:9], off offset:96
	s_nop 1
	v_lshlrev_b32_e32 v7, 16, v3
	v_lshlrev_b32_e32 v6, 16, v2
	v_and_b32_e32 v9, 0xffff0000, v3
	v_and_b32_e32 v8, 0xffff0000, v2
	v_pk_mul_f32 v[2:3], v[0:1], v[6:7] op_sel_hi:[0,1]
	v_mov_b32_e32 v6, v14
	v_mov_b32_e32 v7, v16
	v_pk_mul_f32 v[2:3], v[6:7], v[2:3]
	v_pk_mul_f32 v[6:7], v[0:1], v[8:9] op_sel_hi:[0,1]
	v_lshlrev_b32_e32 v9, 16, v5
	v_lshlrev_b32_e32 v8, 16, v4
	v_and_b32_e32 v5, 0xffff0000, v5
	v_and_b32_e32 v4, 0xffff0000, v4
	v_mov_b32_e32 v16, v15
	v_mov_b32_e32 v15, v12
	v_pk_mul_f32 v[4:5], v[0:1], v[4:5] op_sel_hi:[0,1]
	v_mov_b32_e32 v12, v11
	v_pk_mul_f32 v[6:7], v[16:17], v[6:7]
	v_pk_mul_f32 v[8:9], v[0:1], v[8:9] op_sel_hi:[0,1]
	v_mov_b32_e32 v14, v10
	v_pk_mul_f32 v[4:5], v[12:13], v[4:5]
	v_pk_mul_f32 v[8:9], v[14:15], v[8:9]
	v_bfe_u32 v10, v5, 16, 1
	v_bfe_u32 v11, v4, 16, 1
	v_bfe_u32 v12, v7, 16, 1
	v_bfe_u32 v13, v6, 16, 1
	v_add3_u32 v6, v6, v13, s54
	v_add3_u32 v7, v7, v12, s54
	v_add3_u32 v4, v4, v11, s54
	v_add3_u32 v5, v5, v10, s54
	v_bfe_u32 v10, v2, 16, 1
	v_bfe_u32 v11, v3, 16, 1
	v_bfe_u32 v12, v8, 16, 1
	v_bfe_u32 v13, v9, 16, 1
	v_add3_u32 v9, v9, v13, s54
	v_add3_u32 v8, v8, v12, s54
	v_add3_u32 v3, v3, v11, s54
	v_add3_u32 v2, v2, v10, s54
	v_lshrrev_b32_e32 v2, 16, v2
	v_lshrrev_b32_e32 v3, 16, v3
	v_lshrrev_b32_e32 v8, 16, v8
	v_lshrrev_b32_e32 v9, 16, v9
	v_and_or_b32 v5, v5, s56, v9
	v_and_or_b32 v4, v4, s56, v8
	v_and_or_b32 v3, v7, s56, v3
	v_and_or_b32 v2, v6, s56, v2
	global_store_dwordx4 v[32:33], v[2:5], off offset:112
	global_load_dwordx4 v[2:5], v[32:33], off offset:176
	s_nop 0
	global_load_dwordx4 v[6:9], v[32:33], off offset:160
	global_load_dwordx4 v[14:17], v[32:33], off offset:144
	global_load_dwordx4 v[22:25], v[32:33], off offset:128
	global_load_dwordx4 v[10:13], v1, s[4:5] offset:1072
	global_load_dwordx4 v[18:21], v1, s[4:5] offset:1056
	global_load_dwordx4 v[34:37], v1, s[4:5] offset:1040
	global_load_dwordx4 v[38:41], v1, s[4:5] offset:1024
	s_waitcnt vmcnt(0)
; template <int D, int ROT0, int HALF, bool GAIN, bool KEEP = true>
; DI void chunk_nr(u16* p, const float* __restrict__ gain, const float* __restrict__ tab) {
;     ...
;     } else if (GAIN) {
;       f32x8 x1 = bf8_to_f32(RAWV(v));
;       const f32x8 g1 = *(const f32x8*)(gain + v * 8);
; #pragma unroll
;       for (int e = 0; e < 8; ++e) x1[e] = x1[e] * rstd * g1[e];
;       *(u32x4*)(p + v * 8) = f32_to_bf8(x1);
;     }
	v_lshlrev_b32_e32 v43, 16, v23
	v_lshlrev_b32_e32 v42, 16, v22
	v_and_b32_e32 v23, 0xffff0000, v23
	v_and_b32_e32 v22, 0xffff0000, v22
	v_mov_b32_e32 v44, v38
	v_mov_b32_e32 v45, v40
	v_pk_mul_f32 v[22:23], v[0:1], v[22:23] op_sel_hi:[0,1]
	v_mov_b32_e32 v40, v39
	v_lshlrev_b32_e32 v39, 16, v25
	v_lshlrev_b32_e32 v38, 16, v24
	v_and_b32_e32 v25, 0xffff0000, v25
	v_and_b32_e32 v24, 0xffff0000, v24
	v_pk_mul_f32 v[22:23], v[40:41], v[22:23]
	v_mov_b32_e32 v41, v36
	v_pk_mul_f32 v[24:25], v[0:1], v[24:25] op_sel_hi:[0,1]
	v_mov_b32_e32 v36, v35
	v_pk_mul_f32 v[42:43], v[0:1], v[42:43] op_sel_hi:[0,1]
	v_pk_mul_f32 v[38:39], v[0:1], v[38:39] op_sel_hi:[0,1]
	v_mov_b32_e32 v40, v34
	v_pk_mul_f32 v[24:25], v[36:37], v[24:25]
	v_pk_mul_f32 v[42:43], v[44:45], v[42:43]
	v_pk_mul_f32 v[38:39], v[40:41], v[38:39]
	v_bfe_u32 v34, v25, 16, 1
	v_bfe_u32 v35, v24, 16, 1
	v_bfe_u32 v36, v23, 16, 1
	v_bfe_u32 v37, v22, 16, 1
	v_add3_u32 v22, v22, v37, s54
	v_add3_u32 v23, v23, v36, s54
	v_add3_u32 v24, v24, v35, s54
	v_add3_u32 v25, v25, v34, s54
	v_bfe_u32 v34, v42, 16, 1
	v_bfe_u32 v35, v43, 16, 1
	v_bfe_u32 v36, v38, 16, 1
	v_bfe_u32 v37, v39, 16, 1
	v_add3_u32 v37, v39, v37, s54
	v_add3_u32 v36, v38, v36, s54
	v_add3_u32 v35, v43, v35, s54
	v_add3_u32 v34, v42, v34, s54
	v_lshrrev_b32_e32 v34, 16, v34
	v_lshrrev_b32_e32 v35, 16, v35
	v_lshrrev_b32_e32 v36, 16, v36
	v_lshrrev_b32_e32 v37, 16, v37
	v_and_or_b32 v25, v25, s56, v37
	v_and_or_b32 v24, v24, s56, v36
	v_and_or_b32 v23, v23, s56, v35
	v_and_or_b32 v22, v22, s56, v34
	global_store_dwordx4 v[32:33], v[22:25], off offset:128
	v_lshlrev_b32_e32 v35, 16, v7
	v_lshlrev_b32_e32 v34, 16, v6
	v_lshlrev_b32_e32 v23, 16, v15
	v_lshlrev_b32_e32 v22, 16, v14
	v_and_b32_e32 v25, 0xffff0000, v15
	v_and_b32_e32 v24, 0xffff0000, v14
	v_pk_mul_f32 v[14:15], v[0:1], v[22:23] op_sel_hi:[0,1]
	v_mov_b32_e32 v22, v18
	v_mov_b32_e32 v23, v20
	v_pk_mul_f32 v[14:15], v[22:23], v[14:15]
	v_pk_mul_f32 v[22:23], v[0:1], v[24:25] op_sel_hi:[0,1]
	v_mov_b32_e32 v20, v19
	v_pk_mul_f32 v[18:19], v[20:21], v[22:23]
	v_lshlrev_b32_e32 v21, 16, v17
	v_lshlrev_b32_e32 v20, 16, v16
	v_and_b32_e32 v17, 0xffff0000, v17
	v_and_b32_e32 v16, 0xffff0000, v16
	v_mov_b32_e32 v23, v12
	v_pk_mul_f32 v[16:17], v[0:1], v[16:17] op_sel_hi:[0,1]
	v_mov_b32_e32 v12, v11
	v_pk_mul_f32 v[20:21], v[0:1], v[20:21] op_sel_hi:[0,1]
	v_mov_b32_e32 v22, v10
	v_pk_mul_f32 v[10:11], v[12:13], v[16:17]
	v_pk_mul_f32 v[20:21], v[22:23], v[20:21]
	v_bfe_u32 v12, v11, 16, 1
	v_bfe_u32 v13, v10, 16, 1
	v_bfe_u32 v16, v19, 16, 1
	v_bfe_u32 v17, v18, 16, 1
	v_add3_u32 v17, v18, v17, s54
	v_add3_u32 v16, v19, v16, s54
	v_add3_u32 v10, v10, v13, s54
	v_add3_u32 v11, v11, v12, s54
	v_bfe_u32 v12, v14, 16, 1
	v_bfe_u32 v13, v15, 16, 1
	v_bfe_u32 v18, v20, 16, 1
	v_bfe_u32 v19, v21, 16, 1
	v_add3_u32 v19, v21, v19, s54
	v_add3_u32 v18, v20, v18, s54
	v_add3_u32 v13, v15, v13, s54
	v_add3_u32 v12, v14, v12, s54
	v_lshrrev_b32_e32 v14, 16, v12
	v_lshrrev_b32_e32 v15, 16, v13
	v_lshrrev_b32_e32 v12, 16, v18
	v_lshrrev_b32_e32 v13, 16, v19
	v_and_or_b32 v13, v11, s56, v13
	v_and_or_b32 v12, v10, s56, v12
	v_and_or_b32 v11, v16, s56, v15
	v_and_or_b32 v10, v17, s56, v14
	global_store_dwordx4 v[32:33], v[10:13], off offset:144
	global_load_dwordx4 v[10:13], v1, s[4:5] offset:1136
	s_nop 0
	global_load_dwordx4 v[14:17], v1, s[4:5] offset:1120
	global_load_dwordx4 v[18:21], v1, s[4:5] offset:1104
	global_load_dwordx4 v[22:25], v1, s[4:5] offset:1088
	v_and_b32_e32 v7, 0xffff0000, v7
	v_and_b32_e32 v6, 0xffff0000, v6
	v_pk_mul_f32 v[6:7], v[0:1], v[6:7] op_sel_hi:[0,1]
	v_pk_mul_f32 v[34:35], v[0:1], v[34:35] op_sel_hi:[0,1]
	s_waitcnt vmcnt(0)
	v_mov_b32_e32 v36, v22
	v_mov_b32_e32 v37, v24
	v_mov_b32_e32 v24, v23
	v_lshlrev_b32_e32 v23, 16, v9
	v_lshlrev_b32_e32 v22, 16, v8
	v_and_b32_e32 v9, 0xffff0000, v9
	v_and_b32_e32 v8, 0xffff0000, v8
	v_pk_mul_f32 v[6:7], v[24:25], v[6:7]
	v_mov_b32_e32 v25, v20
	v_pk_mul_f32 v[8:9], v[0:1], v[8:9] op_sel_hi:[0,1]
	v_mov_b32_e32 v20, v19
	v_pk_mul_f32 v[22:23], v[0:1], v[22:23] op_sel_hi:[0,1]
	v_mov_b32_e32 v24, v18
	v_pk_mul_f32 v[8:9], v[20:21], v[8:9]
	v_pk_mul_f32 v[34:35], v[36:37], v[34:35]
	v_pk_mul_f32 v[22:23], v[24:25], v[22:23]
	v_bfe_u32 v18, v9, 16, 1
	v_bfe_u32 v19, v8, 16, 1
	v_bfe_u32 v20, v7, 16, 1
	v_bfe_u32 v21, v6, 16, 1
	v_add3_u32 v6, v6, v21, s54
	v_add3_u32 v7, v7, v20, s54
	v_add3_u32 v8, v8, v19, s54
	v_add3_u32 v9, v9, v18, s54
	v_bfe_u32 v18, v34, 16, 1
	v_bfe_u32 v19, v35, 16, 1
	v_bfe_u32 v20, v22, 16, 1
	v_bfe_u32 v21, v23, 16, 1
	v_add3_u32 v21, v23, v21, s54
	v_add3_u32 v20, v22, v20, s54
	v_add3_u32 v19, v35, v19, s54
	v_add3_u32 v18, v34, v18, s54
	v_lshrrev_b32_e32 v18, 16, v18
	v_lshrrev_b32_e32 v19, 16, v19
	v_lshrrev_b32_e32 v20, 16, v20
	v_lshrrev_b32_e32 v21, 16, v21
	v_and_or_b32 v9, v9, s56, v21
	v_and_or_b32 v8, v8, s56, v20
	v_and_or_b32 v7, v7, s56, v19
	v_and_or_b32 v6, v6, s56, v18
	global_store_dwordx4 v[32:33], v[6:9], off offset:160
	s_nop 1
	v_lshlrev_b32_e32 v7, 16, v3
	v_lshlrev_b32_e32 v6, 16, v2
	v_and_b32_e32 v9, 0xffff0000, v3
	v_and_b32_e32 v8, 0xffff0000, v2
	v_pk_mul_f32 v[2:3], v[0:1], v[6:7] op_sel_hi:[0,1]
	v_mov_b32_e32 v6, v14
	v_mov_b32_e32 v7, v16
	v_pk_mul_f32 v[2:3], v[6:7], v[2:3]
	v_pk_mul_f32 v[6:7], v[0:1], v[8:9] op_sel_hi:[0,1]
	v_lshlrev_b32_e32 v9, 16, v5
	v_lshlrev_b32_e32 v8, 16, v4
	v_and_b32_e32 v5, 0xffff0000, v5
	v_and_b32_e32 v4, 0xffff0000, v4
	v_mov_b32_e32 v16, v15
	v_mov_b32_e32 v15, v12
	v_pk_mul_f32 v[4:5], v[0:1], v[4:5] op_sel_hi:[0,1]
	v_mov_b32_e32 v12, v11
	v_pk_mul_f32 v[6:7], v[16:17], v[6:7]
	v_pk_mul_f32 v[8:9], v[0:1], v[8:9] op_sel_hi:[0,1]
	v_mov_b32_e32 v14, v10
	v_pk_mul_f32 v[4:5], v[12:13], v[4:5]
	v_pk_mul_f32 v[8:9], v[14:15], v[8:9]
	v_bfe_u32 v10, v5, 16, 1
	v_bfe_u32 v11, v4, 16, 1
	v_bfe_u32 v12, v7, 16, 1
	v_bfe_u32 v13, v6, 16, 1
	v_add3_u32 v6, v6, v13, s54
	v_add3_u32 v7, v7, v12, s54
	v_add3_u32 v4, v4, v11, s54
	v_add3_u32 v5, v5, v10, s54
	v_bfe_u32 v10, v2, 16, 1
	v_bfe_u32 v11, v3, 16, 1
	v_bfe_u32 v12, v8, 16, 1
	v_bfe_u32 v13, v9, 16, 1
	v_add3_u32 v9, v9, v13, s54
	v_add3_u32 v8, v8, v12, s54
	v_add3_u32 v3, v3, v11, s54
	v_add3_u32 v2, v2, v10, s54
	v_lshrrev_b32_e32 v2, 16, v2
	v_lshrrev_b32_e32 v3, 16, v3
	v_lshrrev_b32_e32 v8, 16, v8
	v_lshrrev_b32_e32 v9, 16, v9
	v_and_or_b32 v5, v5, s56, v9
	v_and_or_b32 v4, v4, s56, v8
	v_and_or_b32 v3, v7, s56, v3
	v_and_or_b32 v2, v6, s56, v2
	global_store_dwordx4 v[32:33], v[2:5], off offset:176
	global_load_dwordx4 v[2:5], v[32:33], off offset:240
	s_nop 0
	global_load_dwordx4 v[6:9], v[32:33], off offset:224
	global_load_dwordx4 v[14:17], v[32:33], off offset:208
	global_load_dwordx4 v[22:25], v[32:33], off offset:192
	global_load_dwordx4 v[10:13], v1, s[4:5] offset:1200
	global_load_dwordx4 v[18:21], v1, s[4:5] offset:1184
	global_load_dwordx4 v[34:37], v1, s[4:5] offset:1168
	global_load_dwordx4 v[38:41], v1, s[4:5] offset:1152
	s_waitcnt vmcnt(0)
; template <int D, int ROT0, int HALF, bool GAIN, bool KEEP = true>
; DI void chunk_nr(u16* p, const float* __restrict__ gain, const float* __restrict__ tab) {
;     ...
;     } else if (GAIN) {
;       f32x8 x1 = bf8_to_f32(RAWV(v));
;       const f32x8 g1 = *(const f32x8*)(gain + v * 8);
; #pragma unroll
;       for (int e = 0; e < 8; ++e) x1[e] = x1[e] * rstd * g1[e];
;       *(u32x4*)(p + v * 8) = f32_to_bf8(x1);
;     }
	v_lshlrev_b32_e32 v43, 16, v23
	v_lshlrev_b32_e32 v42, 16, v22
	v_and_b32_e32 v23, 0xffff0000, v23
	v_and_b32_e32 v22, 0xffff0000, v22
	v_mov_b32_e32 v44, v38
	v_mov_b32_e32 v45, v40
	v_pk_mul_f32 v[22:23], v[0:1], v[22:23] op_sel_hi:[0,1]
	v_mov_b32_e32 v40, v39
	v_lshlrev_b32_e32 v39, 16, v25
	v_lshlrev_b32_e32 v38, 16, v24
	v_and_b32_e32 v25, 0xffff0000, v25
	v_and_b32_e32 v24, 0xffff0000, v24
	v_pk_mul_f32 v[22:23], v[40:41], v[22:23]
	v_mov_b32_e32 v41, v36
	v_pk_mul_f32 v[24:25], v[0:1], v[24:25] op_sel_hi:[0,1]
	v_mov_b32_e32 v36, v35
	v_pk_mul_f32 v[42:43], v[0:1], v[42:43] op_sel_hi:[0,1]
	v_pk_mul_f32 v[38:39], v[0:1], v[38:39] op_sel_hi:[0,1]
	v_mov_b32_e32 v40, v34
	v_pk_mul_f32 v[24:25], v[36:37], v[24:25]
	v_pk_mul_f32 v[42:43], v[44:45], v[42:43]
	v_pk_mul_f32 v[38:39], v[40:41], v[38:39]
	v_bfe_u32 v34, v25, 16, 1
	v_bfe_u32 v35, v24, 16, 1
	v_bfe_u32 v36, v23, 16, 1
	v_bfe_u32 v37, v22, 16, 1
	v_add3_u32 v22, v22, v37, s54
	v_add3_u32 v23, v23, v36, s54
	v_add3_u32 v24, v24, v35, s54
	v_add3_u32 v25, v25, v34, s54
	v_bfe_u32 v34, v42, 16, 1
	v_bfe_u32 v35, v43, 16, 1
	v_bfe_u32 v36, v38, 16, 1
	v_bfe_u32 v37, v39, 16, 1
	v_add3_u32 v37, v39, v37, s54
	v_add3_u32 v36, v38, v36, s54
	v_add3_u32 v35, v43, v35, s54
	v_add3_u32 v34, v42, v34, s54
	v_lshrrev_b32_e32 v34, 16, v34
	v_lshrrev_b32_e32 v35, 16, v35
	v_lshrrev_b32_e32 v36, 16, v36
	v_lshrrev_b32_e32 v37, 16, v37
	v_and_or_b32 v25, v25, s56, v37
	v_and_or_b32 v24, v24, s56, v36
	v_and_or_b32 v23, v23, s56, v35
	v_and_or_b32 v22, v22, s56, v34
	global_store_dwordx4 v[32:33], v[22:25], off offset:192
	v_lshlrev_b32_e32 v35, 16, v7
	v_lshlrev_b32_e32 v34, 16, v6
	v_lshlrev_b32_e32 v23, 16, v15
	v_lshlrev_b32_e32 v22, 16, v14
	v_and_b32_e32 v25, 0xffff0000, v15
	v_and_b32_e32 v24, 0xffff0000, v14
	v_pk_mul_f32 v[14:15], v[0:1], v[22:23] op_sel_hi:[0,1]
	v_mov_b32_e32 v22, v18
	v_mov_b32_e32 v23, v20
	v_pk_mul_f32 v[14:15], v[22:23], v[14:15]
	v_pk_mul_f32 v[22:23], v[0:1], v[24:25] op_sel_hi:[0,1]
	v_mov_b32_e32 v20, v19
	v_pk_mul_f32 v[18:19], v[20:21], v[22:23]
	v_lshlrev_b32_e32 v21, 16, v17
	v_lshlrev_b32_e32 v20, 16, v16
	v_and_b32_e32 v17, 0xffff0000, v17
	v_and_b32_e32 v16, 0xffff0000, v16
	v_mov_b32_e32 v23, v12
	v_pk_mul_f32 v[16:17], v[0:1], v[16:17] op_sel_hi:[0,1]
	v_mov_b32_e32 v12, v11
	v_pk_mul_f32 v[20:21], v[0:1], v[20:21] op_sel_hi:[0,1]
	v_mov_b32_e32 v22, v10
	v_pk_mul_f32 v[10:11], v[12:13], v[16:17]
	v_pk_mul_f32 v[20:21], v[22:23], v[20:21]
	v_bfe_u32 v12, v11, 16, 1
	v_bfe_u32 v13, v10, 16, 1
	v_bfe_u32 v16, v19, 16, 1
	v_bfe_u32 v17, v18, 16, 1
	v_add3_u32 v17, v18, v17, s54
	v_add3_u32 v16, v19, v16, s54
	v_add3_u32 v10, v10, v13, s54
	v_add3_u32 v11, v11, v12, s54
	v_bfe_u32 v12, v14, 16, 1
	v_bfe_u32 v13, v15, 16, 1
	v_bfe_u32 v18, v20, 16, 1
	v_bfe_u32 v19, v21, 16, 1
	v_add3_u32 v19, v21, v19, s54
	v_add3_u32 v18, v20, v18, s54
	v_add3_u32 v13, v15, v13, s54
	v_add3_u32 v12, v14, v12, s54
	v_lshrrev_b32_e32 v14, 16, v12
	v_lshrrev_b32_e32 v15, 16, v13
	v_lshrrev_b32_e32 v12, 16, v18
	v_lshrrev_b32_e32 v13, 16, v19
	v_and_or_b32 v13, v11, s56, v13
	v_and_or_b32 v12, v10, s56, v12
	v_and_or_b32 v11, v16, s56, v15
	v_and_or_b32 v10, v17, s56, v14
	global_store_dwordx4 v[32:33], v[10:13], off offset:208
	global_load_dwordx4 v[10:13], v1, s[4:5] offset:1264
	s_nop 0
	global_load_dwordx4 v[14:17], v1, s[4:5] offset:1248
	global_load_dwordx4 v[18:21], v1, s[4:5] offset:1232
	global_load_dwordx4 v[22:25], v1, s[4:5] offset:1216
	v_and_b32_e32 v7, 0xffff0000, v7
	v_and_b32_e32 v6, 0xffff0000, v6
	v_pk_mul_f32 v[6:7], v[0:1], v[6:7] op_sel_hi:[0,1]
	v_pk_mul_f32 v[34:35], v[0:1], v[34:35] op_sel_hi:[0,1]
	s_waitcnt vmcnt(0)
	v_mov_b32_e32 v36, v22
	v_mov_b32_e32 v37, v24
	v_mov_b32_e32 v24, v23
	v_lshlrev_b32_e32 v23, 16, v9
	v_lshlrev_b32_e32 v22, 16, v8
	v_and_b32_e32 v9, 0xffff0000, v9
	v_and_b32_e32 v8, 0xffff0000, v8
	v_pk_mul_f32 v[6:7], v[24:25], v[6:7]
	v_mov_b32_e32 v25, v20
	v_pk_mul_f32 v[8:9], v[0:1], v[8:9] op_sel_hi:[0,1]
	v_mov_b32_e32 v20, v19
	v_pk_mul_f32 v[22:23], v[0:1], v[22:23] op_sel_hi:[0,1]
	v_mov_b32_e32 v24, v18
	v_pk_mul_f32 v[8:9], v[20:21], v[8:9]
	v_pk_mul_f32 v[34:35], v[36:37], v[34:35]
	v_pk_mul_f32 v[22:23], v[24:25], v[22:23]
	v_bfe_u32 v18, v9, 16, 1
	v_bfe_u32 v19, v8, 16, 1
	v_bfe_u32 v20, v7, 16, 1
	v_bfe_u32 v21, v6, 16, 1
	v_add3_u32 v6, v6, v21, s54
	v_add3_u32 v7, v7, v20, s54
	v_add3_u32 v8, v8, v19, s54
	v_add3_u32 v9, v9, v18, s54
	v_bfe_u32 v18, v34, 16, 1
	v_bfe_u32 v19, v35, 16, 1
	v_bfe_u32 v20, v22, 16, 1
	v_bfe_u32 v21, v23, 16, 1
	v_add3_u32 v21, v23, v21, s54
	v_add3_u32 v20, v22, v20, s54
	v_add3_u32 v19, v35, v19, s54
	v_add3_u32 v18, v34, v18, s54
	v_lshrrev_b32_e32 v18, 16, v18
	v_lshrrev_b32_e32 v19, 16, v19
	v_lshrrev_b32_e32 v20, 16, v20
	v_lshrrev_b32_e32 v21, 16, v21
	v_and_or_b32 v9, v9, s56, v21
	v_and_or_b32 v8, v8, s56, v20
	v_and_or_b32 v7, v7, s56, v19
	v_and_or_b32 v6, v6, s56, v18
	global_store_dwordx4 v[32:33], v[6:9], off offset:224
	s_nop 1
	v_lshlrev_b32_e32 v7, 16, v3
	v_lshlrev_b32_e32 v6, 16, v2
	v_and_b32_e32 v9, 0xffff0000, v3
	v_and_b32_e32 v8, 0xffff0000, v2
	v_pk_mul_f32 v[2:3], v[0:1], v[6:7] op_sel_hi:[0,1]
	v_mov_b32_e32 v6, v14
	v_mov_b32_e32 v7, v16
	v_pk_mul_f32 v[2:3], v[6:7], v[2:3]
	v_pk_mul_f32 v[6:7], v[0:1], v[8:9] op_sel_hi:[0,1]
	v_lshlrev_b32_e32 v9, 16, v5
	v_lshlrev_b32_e32 v8, 16, v4
	v_and_b32_e32 v5, 0xffff0000, v5
	v_and_b32_e32 v4, 0xffff0000, v4
	v_mov_b32_e32 v16, v15
	v_mov_b32_e32 v15, v12
	v_pk_mul_f32 v[4:5], v[0:1], v[4:5] op_sel_hi:[0,1]
	v_mov_b32_e32 v12, v11
	v_pk_mul_f32 v[6:7], v[16:17], v[6:7]
	v_pk_mul_f32 v[8:9], v[0:1], v[8:9] op_sel_hi:[0,1]
; template <int D, int ROT0, int HALF, bool GAIN, bool KEEP = true>
; DI void chunk_nr(u16* p, const float* __restrict__ gain, const float* __restrict__ tab) {
;     ...
;     if (v >= V0 && v < V0 + 2 * NRV) {
;       if (v >= V0 + NRV) continue;
;       const f32x8 x1 = bf8_to_f32(RAWV(v));
;       const f32x8 x2 = bf8_to_f32(RAWV(v + NRV));
;       f32x8 g1, g2;
;       if (GAIN) { g1 = *(const f32x8*)(gain + v * 8); g2 = *(const f32x8*)(gain + (v + NRV) * 8); }
;       const f32x8 t0 = *(const f32x8*)(tab + 2 * (v - V0) * 8);
;       const f32x8 t1 = *(const f32x8*)(tab + 2 * (v - V0) * 8 + 8);
;       f32x8 o1, o2;
; #pragma unroll
;       for (int e = 0; e < 8; ++e) {
;         float y1 = x1[e], y2 = x2[e];
;         if (GAIN) { y1 = y1 * rstd * g1[e]; y2 = y2 * rstd * g2[e]; }
;         const float c = (e < 4) ? t0[2 * e] : t1[2 * (e - 4)];
;         const float sn = (e < 4) ? t0[2 * e + 1] : t1[2 * (e - 4) + 1];
;         o1[e] = y1 * c - y2 * sn;
;         o2[e] = y2 * c + y1 * sn;
;       }
;       *(u32x4*)(p + v * 8) = f32_to_bf8(o1);
;       *(u32x4*)(p + (v + NRV) * 8) = f32_to_bf8(o2);
;     } else if (GAIN) {
;       f32x8 x1 = bf8_to_f32(RAWV(v));
;       const f32x8 g1 = *(const f32x8*)(gain + v * 8);
; #pragma unroll
;       for (int e = 0; e < 8; ++e) x1[e] = x1[e] * rstd * g1[e];
;       *(u32x4*)(p + v * 8) = f32_to_bf8(x1);
;     }
	v_mov_b32_e32 v14, v10
	v_pk_mul_f32 v[4:5], v[12:13], v[4:5]
	v_pk_mul_f32 v[8:9], v[14:15], v[8:9]
	v_bfe_u32 v10, v5, 16, 1
	v_bfe_u32 v11, v4, 16, 1
	v_bfe_u32 v12, v7, 16, 1
	v_bfe_u32 v13, v6, 16, 1
	v_add3_u32 v6, v6, v13, s54
	v_add3_u32 v7, v7, v12, s54
	v_add3_u32 v4, v4, v11, s54
	v_add3_u32 v5, v5, v10, s54
	v_bfe_u32 v10, v2, 16, 1
	v_bfe_u32 v11, v3, 16, 1
	v_bfe_u32 v12, v8, 16, 1
	v_bfe_u32 v13, v9, 16, 1
	v_add3_u32 v9, v9, v13, s54
	v_add3_u32 v8, v8, v12, s54
	v_add3_u32 v3, v3, v11, s54
	v_add3_u32 v2, v2, v10, s54
	v_lshrrev_b32_e32 v2, 16, v2
	v_lshrrev_b32_e32 v3, 16, v3
	v_lshrrev_b32_e32 v8, 16, v8
	v_lshrrev_b32_e32 v9, 16, v9
	v_and_or_b32 v5, v5, s56, v9
	v_and_or_b32 v4, v4, s56, v8
	v_and_or_b32 v3, v7, s56, v3
	v_and_or_b32 v2, v6, s56, v2
	global_store_dwordx4 v[32:33], v[2:5], off offset:240
	global_load_dwordx4 v[10:13], v[32:33], off offset:256
	global_load_dwordx4 v[14:17], v[32:33], off offset:320
	global_load_dwordx4 v[34:37], v1, s[4:5] offset:1408
	global_load_dwordx4 v[38:41], v1, s[4:5] offset:1280
	global_load_dwordx4 v[42:45], v[28:29], off offset:192
	global_load_dwordx4 v[46:49], v[28:29], off offset:208
	global_load_dwordx4 v[50:53], v1, s[4:5] offset:1424
	global_load_dwordx4 v[54:57], v1, s[4:5] offset:1296
	global_load_dwordx4 v[58:61], v[28:29], off offset:224
	global_load_dwordx4 v[62:65], v[28:29], off offset:240
	global_load_dwordx4 v[22:25], v[32:33], off offset:272
	global_load_dwordx4 v[18:21], v[32:33], off offset:336
	global_load_dwordx4 v[2:5], v1, s[4:5] offset:1328
	global_load_dwordx4 v[66:69], v1, s[4:5] offset:1312
	global_load_dwordx4 v[6:9], v1, s[4:5] offset:1456
	global_load_dwordx4 v[70:73], v1, s[4:5] offset:1440
	s_waitcnt vmcnt(0)
	v_lshlrev_b32_e32 v75, 16, v11
	v_lshlrev_b32_e32 v77, 16, v15
	v_lshlrev_b32_e32 v76, 16, v14
	v_and_b32_e32 v15, 0xffff0000, v15
	v_and_b32_e32 v14, 0xffff0000, v14
	v_mov_b32_e32 v80, v38
	v_mov_b32_e32 v81, v40
	v_mov_b32_e32 v40, v39
	v_mov_b32_e32 v38, v44
	v_mov_b32_e32 v39, v48
	v_mov_b32_e32 v48, v45
	v_lshlrev_b32_e32 v45, 16, v17
	v_lshlrev_b32_e32 v44, 16, v16
	v_and_b32_e32 v17, 0xffff0000, v17
	v_and_b32_e32 v16, 0xffff0000, v16
	v_lshlrev_b32_e32 v74, 16, v10
	v_and_b32_e32 v11, 0xffff0000, v11
	v_and_b32_e32 v10, 0xffff0000, v10
	v_mov_b32_e32 v78, v34
	v_mov_b32_e32 v79, v36
	v_mov_b32_e32 v36, v35
	v_mov_b32_e32 v34, v42
	v_mov_b32_e32 v35, v46
	v_mov_b32_e32 v46, v43
	v_lshlrev_b32_e32 v43, 16, v13
	v_lshlrev_b32_e32 v42, 16, v12
	v_and_b32_e32 v13, 0xffff0000, v13
	v_and_b32_e32 v12, 0xffff0000, v12
	v_mov_b32_e32 v83, v52
	v_mov_b32_e32 v52, v51
	v_pk_mul_f32 v[14:15], v[0:1], v[14:15] op_sel_hi:[0,1]
	v_pk_mul_f32 v[16:17], v[0:1], v[16:17] op_sel_hi:[0,1]
	v_mov_b32_e32 v82, v50
	v_mov_b32_e32 v85, v56
	v_mov_b32_e32 v56, v55
	v_mov_b32_e32 v50, v58
	v_mov_b32_e32 v51, v62
	v_mov_b32_e32 v62, v59
	v_mov_b32_e32 v55, v64
	v_mov_b32_e32 v64, v61
	v_pk_mul_f32 v[58:59], v[0:1], v[76:77] op_sel_hi:[0,1]
	v_pk_mul_f32 v[10:11], v[0:1], v[10:11] op_sel_hi:[0,1]
	v_pk_mul_f32 v[44:45], v[0:1], v[44:45] op_sel_hi:[0,1]
	v_pk_mul_f32 v[12:13], v[0:1], v[12:13] op_sel_hi:[0,1]
	v_pk_mul_f32 v[14:15], v[36:37], v[14:15]
	v_pk_mul_f32 v[16:17], v[52:53], v[16:17]
	v_mov_b32_e32 v84, v54
	v_mov_b32_e32 v54, v60
	v_pk_mul_f32 v[60:61], v[0:1], v[74:75] op_sel_hi:[0,1]
	v_pk_mul_f32 v[42:43], v[0:1], v[42:43] op_sel_hi:[0,1]
	v_pk_mul_f32 v[58:59], v[78:79], v[58:59]
	v_pk_mul_f32 v[36:37], v[40:41], v[10:11]
	v_pk_mul_f32 v[40:41], v[82:83], v[44:45]
	v_pk_mul_f32 v[44:45], v[56:57], v[12:13]
	v_pk_mul_f32 v[12:13], v[48:49], v[14:15]
	v_pk_mul_f32 v[56:57], v[64:65], v[16:17]
	v_pk_mul_f32 v[60:61], v[80:81], v[60:61]
	v_pk_mul_f32 v[42:43], v[84:85], v[42:43]
	v_pk_mul_f32 v[10:11], v[46:47], v[58:59]
	v_pk_mul_f32 v[52:53], v[62:63], v[40:41]
	v_pk_fma_f32 v[12:13], v[38:39], v[36:37], v[12:13] neg_lo:[0,0,1] neg_hi:[0,0,1]
	v_pk_fma_f32 v[56:57], v[54:55], v[44:45], v[56:57] neg_lo:[0,0,1] neg_hi:[0,0,1]
	v_pk_fma_f32 v[10:11], v[34:35], v[60:61], v[10:11] neg_lo:[0,0,1] neg_hi:[0,0,1]
	v_pk_fma_f32 v[52:53], v[50:51], v[42:43], v[52:53] neg_lo:[0,0,1] neg_hi:[0,0,1]
	v_bfe_u32 v74, v57, 16, 1
	v_bfe_u32 v75, v56, 16, 1
	v_bfe_u32 v76, v13, 16, 1
	v_bfe_u32 v77, v12, 16, 1
	v_add3_u32 v77, v12, v77, s54
	v_add3_u32 v76, v13, v76, s54
	v_add3_u32 v12, v56, v75, s54
	v_add3_u32 v13, v57, v74, s54
	v_bfe_u32 v56, v10, 16, 1
	v_bfe_u32 v57, v11, 16, 1
	v_bfe_u32 v74, v52, 16, 1
	v_bfe_u32 v75, v53, 16, 1
	v_add3_u32 v53, v53, v75, s54
	v_add3_u32 v52, v52, v74, s54
	v_add3_u32 v11, v11, v57, s54
	v_add3_u32 v10, v10, v56, s54
	v_lshrrev_b32_e32 v10, 16, v10
	v_lshrrev_b32_e32 v11, 16, v11
	v_lshrrev_b32_e32 v52, 16, v52
	v_lshrrev_b32_e32 v53, 16, v53
	v_and_or_b32 v13, v13, s56, v53
	v_and_or_b32 v12, v12, s56, v52
	v_and_or_b32 v11, v76, s56, v11
	v_and_or_b32 v10, v77, s56, v10
	global_store_dwordx4 v[32:33], v[10:13], off offset:256
	v_lshlrev_b32_e32 v53, 16, v19
	v_lshlrev_b32_e32 v52, 16, v18
	v_pk_mul_f32 v[10:11], v[46:47], v[60:61]
	v_pk_mul_f32 v[12:13], v[48:49], v[36:37]
	v_pk_fma_f32 v[10:11], v[34:35], v[58:59], v[10:11]
	v_pk_mul_f32 v[34:35], v[64:65], v[44:45]
	v_pk_fma_f32 v[12:13], v[38:39], v[14:15], v[12:13]
	v_pk_mul_f32 v[14:15], v[62:63], v[42:43]
	v_pk_fma_f32 v[16:17], v[54:55], v[16:17], v[34:35]
	v_pk_fma_f32 v[14:15], v[50:51], v[40:41], v[14:15]
	v_bfe_u32 v34, v17, 16, 1
	v_bfe_u32 v35, v16, 16, 1
	v_bfe_u32 v36, v13, 16, 1
	v_bfe_u32 v37, v12, 16, 1
	v_add3_u32 v37, v12, v37, s54
	v_add3_u32 v36, v13, v36, s54
	v_add3_u32 v12, v16, v35, s54
	v_add3_u32 v13, v17, v34, s54
	v_bfe_u32 v16, v10, 16, 1
; template <int D, int ROT0, int HALF, bool GAIN, bool KEEP = true>
; DI void chunk_nr(u16* p, const float* __restrict__ gain, const float* __restrict__ tab) {
;     ...
;     if (v >= V0 && v < V0 + 2 * NRV) {
;       if (v >= V0 + NRV) continue;
;       const f32x8 x1 = bf8_to_f32(RAWV(v));
;       const f32x8 x2 = bf8_to_f32(RAWV(v + NRV));
;       f32x8 g1, g2;
;       if (GAIN) { g1 = *(const f32x8*)(gain + v * 8); g2 = *(const f32x8*)(gain + (v + NRV) * 8); }
;       const f32x8 t0 = *(const f32x8*)(tab + 2 * (v - V0) * 8);
;       const f32x8 t1 = *(const f32x8*)(tab + 2 * (v - V0) * 8 + 8);
;       f32x8 o1, o2;
; #pragma unroll
;       for (int e = 0; e < 8; ++e) {
;         float y1 = x1[e], y2 = x2[e];
;         if (GAIN) { y1 = y1 * rstd * g1[e]; y2 = y2 * rstd * g2[e]; }
;         const float c = (e < 4) ? t0[2 * e] : t1[2 * (e - 4)];
;         const float sn = (e < 4) ? t0[2 * e + 1] : t1[2 * (e - 4) + 1];
;         o1[e] = y1 * c - y2 * sn;
;         o2[e] = y2 * c + y1 * sn;
;       }
;       *(u32x4*)(p + v * 8) = f32_to_bf8(o1);
;       *(u32x4*)(p + (v + NRV) * 8) = f32_to_bf8(o2);
	v_bfe_u32 v17, v11, 16, 1
	v_bfe_u32 v34, v14, 16, 1
	v_bfe_u32 v35, v15, 16, 1
	v_add3_u32 v15, v15, v35, s54
	v_add3_u32 v14, v14, v34, s54
	v_add3_u32 v11, v11, v17, s54
	v_add3_u32 v10, v10, v16, s54
	v_lshrrev_b32_e32 v10, 16, v10
	v_lshrrev_b32_e32 v11, 16, v11
	v_lshrrev_b32_e32 v14, 16, v14
	v_lshrrev_b32_e32 v15, 16, v15
	v_and_or_b32 v13, v13, s56, v15
	v_and_or_b32 v12, v12, s56, v14
	v_and_or_b32 v11, v36, s56, v11
	v_and_or_b32 v10, v37, s56, v10
	global_store_dwordx4 v[32:33], v[10:13], off offset:320
	global_load_dwordx4 v[34:37], v[28:29], off offset:256
	global_load_dwordx4 v[38:41], v[28:29], off offset:272
	global_load_dwordx4 v[42:45], v[28:29], off offset:288
	global_load_dwordx4 v[46:49], v[28:29], off offset:304
	global_load_dwordx4 v[14:17], v[32:33], off offset:288
	global_load_dwordx4 v[10:13], v[32:33], off offset:352
	v_and_b32_e32 v19, 0xffff0000, v19
	v_and_b32_e32 v18, 0xffff0000, v18
	v_lshlrev_b32_e32 v61, 16, v21
	v_lshlrev_b32_e32 v60, 16, v20
	v_and_b32_e32 v21, 0xffff0000, v21
	v_and_b32_e32 v20, 0xffff0000, v20
	v_lshlrev_b32_e32 v51, 16, v23
	v_lshlrev_b32_e32 v50, 16, v22
	v_and_b32_e32 v23, 0xffff0000, v23
	v_and_b32_e32 v22, 0xffff0000, v22
	v_mov_b32_e32 v54, v70
	v_mov_b32_e32 v55, v72
	v_mov_b32_e32 v72, v71
	v_pk_mul_f32 v[52:53], v[0:1], v[52:53] op_sel_hi:[0,1]
	v_pk_mul_f32 v[18:19], v[0:1], v[18:19] op_sel_hi:[0,1]
	v_lshlrev_b32_e32 v59, 16, v25
	v_lshlrev_b32_e32 v58, 16, v24
	v_and_b32_e32 v25, 0xffff0000, v25
	v_and_b32_e32 v24, 0xffff0000, v24
	v_pk_mul_f32 v[60:61], v[0:1], v[60:61] op_sel_hi:[0,1]
	v_mov_b32_e32 v62, v6
	v_mov_b32_e32 v63, v8
	v_pk_mul_f32 v[20:21], v[0:1], v[20:21] op_sel_hi:[0,1]
	v_mov_b32_e32 v8, v7
	v_mov_b32_e32 v57, v68
	v_mov_b32_e32 v68, v67
	v_pk_mul_f32 v[22:23], v[0:1], v[22:23] op_sel_hi:[0,1]
	v_pk_mul_f32 v[52:53], v[54:55], v[52:53]
	v_pk_mul_f32 v[18:19], v[72:73], v[18:19]
	v_pk_mul_f32 v[60:61], v[62:63], v[60:61]
	v_mov_b32_e32 v63, v4
	v_pk_mul_f32 v[6:7], v[8:9], v[20:21]
	v_pk_mul_f32 v[8:9], v[0:1], v[24:25] op_sel_hi:[0,1]
	v_mov_b32_e32 v4, v3
	v_mov_b32_e32 v56, v66
	v_pk_mul_f32 v[50:51], v[0:1], v[50:51] op_sel_hi:[0,1]
	v_pk_mul_f32 v[22:23], v[68:69], v[22:23]
	v_pk_mul_f32 v[58:59], v[0:1], v[58:59] op_sel_hi:[0,1]
	v_mov_b32_e32 v62, v2
	v_pk_mul_f32 v[8:9], v[4:5], v[8:9]
	v_pk_mul_f32 v[50:51], v[56:57], v[50:51]
	v_pk_mul_f32 v[58:59], v[62:63], v[58:59]
	s_waitcnt vmcnt(0)
	v_mov_b32_e32 v54, v34
	v_mov_b32_e32 v55, v38
	v_mov_b32_e32 v38, v35
	v_mov_b32_e32 v35, v40
	v_mov_b32_e32 v40, v37
	v_mov_b32_e32 v25, v48
	v_mov_b32_e32 v48, v45
	v_mov_b32_e32 v34, v36
	v_pk_mul_f32 v[36:37], v[40:41], v[18:19]
	v_mov_b32_e32 v21, v46
	v_mov_b32_e32 v46, v43
	v_mov_b32_e32 v24, v44
	v_pk_mul_f32 v[4:5], v[48:49], v[6:7]
	v_pk_mul_f32 v[56:57], v[38:39], v[52:53]
	v_pk_fma_f32 v[36:37], v[34:35], v[22:23], v[36:37] neg_lo:[0,0,1] neg_hi:[0,0,1]
	v_mov_b32_e32 v20, v42
	v_pk_mul_f32 v[2:3], v[46:47], v[60:61]
	v_pk_fma_f32 v[4:5], v[24:25], v[8:9], v[4:5] neg_lo:[0,0,1] neg_hi:[0,0,1]
	v_pk_fma_f32 v[56:57], v[54:55], v[50:51], v[56:57] neg_lo:[0,0,1] neg_hi:[0,0,1]
	v_pk_fma_f32 v[2:3], v[20:21], v[58:59], v[2:3] neg_lo:[0,0,1] neg_hi:[0,0,1]
	v_bfe_u32 v42, v5, 16, 1
	v_bfe_u32 v43, v4, 16, 1
	v_bfe_u32 v44, v37, 16, 1
	v_bfe_u32 v45, v36, 16, 1
	v_add3_u32 v36, v36, v45, s54
	v_add3_u32 v37, v37, v44, s54
	v_add3_u32 v4, v4, v43, s54
	v_add3_u32 v5, v5, v42, s54
	v_bfe_u32 v42, v56, 16, 1
	v_bfe_u32 v43, v57, 16, 1
	v_bfe_u32 v44, v2, 16, 1
	v_bfe_u32 v45, v3, 16, 1
	v_add3_u32 v3, v3, v45, s54
	v_add3_u32 v2, v2, v44, s54
	v_add3_u32 v43, v57, v43, s54
	v_add3_u32 v42, v56, v42, s54
	v_lshrrev_b32_e32 v42, 16, v42
	v_lshrrev_b32_e32 v43, 16, v43
	v_lshrrev_b32_e32 v2, 16, v2
	v_lshrrev_b32_e32 v3, 16, v3
	v_and_or_b32 v5, v5, s56, v3
	v_and_or_b32 v4, v4, s56, v2
	v_and_or_b32 v3, v37, s56, v43
	v_and_or_b32 v2, v36, s56, v42
	global_store_dwordx4 v[32:33], v[2:5], off offset:272
	v_pk_mul_f32 v[8:9], v[48:49], v[8:9]
	v_lshlrev_b32_e32 v77, 16, v11
	v_pk_mul_f32 v[4:5], v[40:41], v[22:23]
	v_pk_mul_f32 v[2:3], v[38:39], v[50:51]
	v_pk_fma_f32 v[4:5], v[34:35], v[18:19], v[4:5]
	v_pk_mul_f32 v[18:19], v[46:47], v[58:59]
	v_pk_fma_f32 v[6:7], v[24:25], v[6:7], v[8:9]
	v_pk_fma_f32 v[2:3], v[54:55], v[52:53], v[2:3]
	v_pk_fma_f32 v[18:19], v[20:21], v[60:61], v[18:19]
	v_bfe_u32 v8, v7, 16, 1
	v_bfe_u32 v9, v6, 16, 1
	v_bfe_u32 v20, v5, 16, 1
	v_bfe_u32 v21, v4, 16, 1
	v_add3_u32 v21, v4, v21, s54
	v_add3_u32 v20, v5, v20, s54
	v_add3_u32 v4, v6, v9, s54
	v_add3_u32 v5, v7, v8, s54
	v_bfe_u32 v6, v2, 16, 1
	v_bfe_u32 v7, v3, 16, 1
	v_bfe_u32 v8, v18, 16, 1
	v_bfe_u32 v9, v19, 16, 1
	v_add3_u32 v9, v19, v9, s54
	v_add3_u32 v8, v18, v8, s54
	v_add3_u32 v3, v3, v7, s54
	v_add3_u32 v2, v2, v6, s54
	v_lshrrev_b32_e32 v2, 16, v2
	v_lshrrev_b32_e32 v3, 16, v3
	v_lshrrev_b32_e32 v6, 16, v8
	v_lshrrev_b32_e32 v7, 16, v9
	v_and_or_b32 v5, v5, s56, v7
	v_and_or_b32 v4, v4, s56, v6
	v_and_or_b32 v3, v20, s56, v3
	v_and_or_b32 v2, v21, s56, v2
	global_store_dwordx4 v[32:33], v[2:5], off offset:336
	global_load_dwordx4 v[6:9], v1, s[4:5] offset:1472
	global_load_dwordx4 v[18:21], v1, s[4:5] offset:1344
	global_load_dwordx4 v[22:25], v[28:29], off offset:320
	global_load_dwordx4 v[34:37], v[28:29], off offset:336
	global_load_dwordx4 v[38:41], v1, s[4:5] offset:1488
	global_load_dwordx4 v[42:45], v1, s[4:5] offset:1360
	global_load_dwordx4 v[46:49], v[28:29], off offset:352
	global_load_dwordx4 v[50:53], v[28:29], off offset:368
	global_load_dwordx4 v[54:57], v[32:33], off offset:304
	global_load_dwordx4 v[58:61], v[32:33], off offset:368
	global_load_dwordx4 v[2:5], v1, s[4:5] offset:1392
	global_load_dwordx4 v[62:65], v1, s[4:5] offset:1376
	global_load_dwordx4 v[66:69], v1, s[4:5] offset:1520
	global_load_dwordx4 v[70:73], v1, s[4:5] offset:1504
	v_lshlrev_b32_e32 v76, 16, v10
	v_lshlrev_b32_e32 v75, 16, v15
	v_lshlrev_b32_e32 v74, 16, v14
	v_and_b32_e32 v15, 0xffff0000, v15
	v_and_b32_e32 v14, 0xffff0000, v14
	v_pk_mul_f32 v[76:77], v[0:1], v[76:77] op_sel_hi:[0,1]
	v_and_b32_e32 v11, 0xffff0000, v11
	v_and_b32_e32 v10, 0xffff0000, v10
	v_pk_mul_f32 v[74:75], v[0:1], v[74:75] op_sel_hi:[0,1]
	v_pk_mul_f32 v[10:11], v[0:1], v[10:11] op_sel_hi:[0,1]
	s_waitcnt vmcnt(0)
; template <int D, int ROT0, int HALF, bool GAIN, bool KEEP = true>
; DI void chunk_nr(u16* p, const float* __restrict__ gain, const float* __restrict__ tab) {
;     ...
;     if (v >= V0 && v < V0 + 2 * NRV) {
;       if (v >= V0 + NRV) continue;
;       const f32x8 x1 = bf8_to_f32(RAWV(v));
;       const f32x8 x2 = bf8_to_f32(RAWV(v + NRV));
;       f32x8 g1, g2;
;       if (GAIN) { g1 = *(const f32x8*)(gain + v * 8); g2 = *(const f32x8*)(gain + (v + NRV) * 8); }
;       const f32x8 t0 = *(const f32x8*)(tab + 2 * (v - V0) * 8);
;       const f32x8 t1 = *(const f32x8*)(tab + 2 * (v - V0) * 8 + 8);
;       f32x8 o1, o2;
; #pragma unroll
;       for (int e = 0; e < 8; ++e) {
;         float y1 = x1[e], y2 = x2[e];
;         if (GAIN) { y1 = y1 * rstd * g1[e]; y2 = y2 * rstd * g2[e]; }
;         const float c = (e < 4) ? t0[2 * e] : t1[2 * (e - 4)];
;         const float sn = (e < 4) ? t0[2 * e + 1] : t1[2 * (e - 4) + 1];
;         o1[e] = y1 * c - y2 * sn;
;         o2[e] = y2 * c + y1 * sn;
;       }
;       *(u32x4*)(p + v * 8) = f32_to_bf8(o1);
;       *(u32x4*)(p + (v + NRV) * 8) = f32_to_bf8(o2);
	v_mov_b32_e32 v78, v6
	v_mov_b32_e32 v79, v8
	v_pk_mul_f32 v[76:77], v[78:79], v[76:77]
	v_mov_b32_e32 v79, v20
	v_mov_b32_e32 v8, v7
	v_pk_mul_f32 v[6:7], v[0:1], v[14:15] op_sel_hi:[0,1]
	v_mov_b32_e32 v20, v19
	v_mov_b32_e32 v78, v18
	v_pk_mul_f32 v[14:15], v[20:21], v[6:7]
	v_mov_b32_e32 v20, v24
	v_mov_b32_e32 v21, v36
	v_mov_b32_e32 v36, v25
	v_lshlrev_b32_e32 v25, 16, v13
	v_lshlrev_b32_e32 v24, 16, v12
	v_and_b32_e32 v13, 0xffff0000, v13
	v_and_b32_e32 v12, 0xffff0000, v12
	v_pk_mul_f32 v[74:75], v[78:79], v[74:75]
	v_mov_b32_e32 v18, v22
	v_mov_b32_e32 v19, v34
	v_mov_b32_e32 v34, v23
	v_lshlrev_b32_e32 v23, 16, v17
	v_lshlrev_b32_e32 v22, 16, v16
	v_and_b32_e32 v17, 0xffff0000, v17
	v_and_b32_e32 v16, 0xffff0000, v16
	v_pk_mul_f32 v[24:25], v[0:1], v[24:25] op_sel_hi:[0,1]
	v_mov_b32_e32 v78, v38
	v_mov_b32_e32 v79, v40
	v_pk_mul_f32 v[12:13], v[0:1], v[12:13] op_sel_hi:[0,1]
	v_mov_b32_e32 v40, v39
	v_pk_mul_f32 v[10:11], v[8:9], v[10:11]
	v_pk_mul_f32 v[24:25], v[78:79], v[24:25]
	v_mov_b32_e32 v79, v44
	v_pk_mul_f32 v[12:13], v[40:41], v[12:13]
	v_pk_mul_f32 v[16:17], v[0:1], v[16:17] op_sel_hi:[0,1]
	v_mov_b32_e32 v44, v43
	v_mov_b32_e32 v43, v52
	v_mov_b32_e32 v52, v49
	v_pk_mul_f32 v[8:9], v[36:37], v[10:11]
	v_pk_mul_f32 v[22:23], v[0:1], v[22:23] op_sel_hi:[0,1]
	v_mov_b32_e32 v78, v42
	v_pk_mul_f32 v[16:17], v[44:45], v[16:17]
	v_mov_b32_e32 v39, v50
	v_mov_b32_e32 v50, v47
	v_mov_b32_e32 v42, v48
	v_pk_mul_f32 v[44:45], v[52:53], v[12:13]
	v_pk_mul_f32 v[6:7], v[34:35], v[76:77]
	v_pk_fma_f32 v[8:9], v[20:21], v[14:15], v[8:9] neg_lo:[0,0,1] neg_hi:[0,0,1]
	v_pk_mul_f32 v[22:23], v[78:79], v[22:23]
	v_mov_b32_e32 v38, v46
	v_pk_mul_f32 v[40:41], v[50:51], v[24:25]
	v_pk_fma_f32 v[44:45], v[42:43], v[16:17], v[44:45] neg_lo:[0,0,1] neg_hi:[0,0,1]
	v_pk_fma_f32 v[6:7], v[18:19], v[74:75], v[6:7] neg_lo:[0,0,1] neg_hi:[0,0,1]
	v_pk_fma_f32 v[40:41], v[38:39], v[22:23], v[40:41] neg_lo:[0,0,1] neg_hi:[0,0,1]
	v_bfe_u32 v46, v45, 16, 1
	v_bfe_u32 v47, v44, 16, 1
	v_bfe_u32 v48, v9, 16, 1
	v_bfe_u32 v49, v8, 16, 1
	v_add3_u32 v49, v8, v49, s54
	v_add3_u32 v48, v9, v48, s54
	v_add3_u32 v8, v44, v47, s54
	v_add3_u32 v9, v45, v46, s54
	v_bfe_u32 v44, v6, 16, 1
	v_bfe_u32 v45, v7, 16, 1
	v_bfe_u32 v46, v40, 16, 1
	v_bfe_u32 v47, v41, 16, 1
	v_add3_u32 v41, v41, v47, s54
	v_add3_u32 v40, v40, v46, s54
	v_add3_u32 v7, v7, v45, s54
	v_add3_u32 v6, v6, v44, s54
	v_lshrrev_b32_e32 v6, 16, v6
	v_lshrrev_b32_e32 v7, 16, v7
	v_lshrrev_b32_e32 v40, 16, v40
	v_lshrrev_b32_e32 v41, 16, v41
	v_and_or_b32 v9, v9, s56, v41
	v_and_or_b32 v8, v8, s56, v40
	v_and_or_b32 v7, v48, s56, v7
	v_and_or_b32 v6, v49, s56, v6
	global_store_dwordx4 v[32:33], v[6:9], off offset:288
	v_lshlrev_b32_e32 v47, 16, v61
	v_lshlrev_b32_e32 v46, 16, v60
	v_pk_mul_f32 v[8:9], v[36:37], v[14:15]
	v_pk_mul_f32 v[14:15], v[52:53], v[16:17]
	v_pk_mul_f32 v[6:7], v[34:35], v[74:75]
	v_pk_fma_f32 v[8:9], v[20:21], v[10:11], v[8:9]
	v_pk_mul_f32 v[10:11], v[50:51], v[22:23]
	v_pk_fma_f32 v[12:13], v[42:43], v[12:13], v[14:15]
	v_pk_fma_f32 v[6:7], v[18:19], v[76:77], v[6:7]
	v_pk_fma_f32 v[10:11], v[38:39], v[24:25], v[10:11]
	v_bfe_u32 v14, v13, 16, 1
	v_bfe_u32 v15, v12, 16, 1
	v_bfe_u32 v16, v9, 16, 1
	v_bfe_u32 v17, v8, 16, 1
	v_add3_u32 v17, v8, v17, s54
	v_add3_u32 v16, v9, v16, s54
	v_add3_u32 v8, v12, v15, s54
	v_add3_u32 v9, v13, v14, s54
	v_bfe_u32 v12, v6, 16, 1
	v_bfe_u32 v13, v7, 16, 1
	v_bfe_u32 v14, v10, 16, 1
	v_bfe_u32 v15, v11, 16, 1
	v_add3_u32 v11, v11, v15, s54
	v_add3_u32 v10, v10, v14, s54
	v_add3_u32 v7, v7, v13, s54
	v_add3_u32 v6, v6, v12, s54
	v_lshrrev_b32_e32 v6, 16, v6
	v_lshrrev_b32_e32 v7, 16, v7
	v_lshrrev_b32_e32 v10, 16, v10
	v_lshrrev_b32_e32 v11, 16, v11
	v_and_or_b32 v9, v9, s56, v11
	v_and_or_b32 v8, v8, s56, v10
	v_and_or_b32 v7, v16, s56, v7
	v_and_or_b32 v6, v17, s56, v6
	global_store_dwordx4 v[32:33], v[6:9], off offset:352
	global_load_dwordx4 v[6:9], v[28:29], off offset:384
	s_nop 0
	global_load_dwordx4 v[10:13], v[28:29], off offset:400
	global_load_dwordx4 v[14:17], v[28:29], off offset:416
	global_load_dwordx4 v[18:21], v[28:29], off offset:432
	v_lshlrev_b32_e32 v35, 16, v59
	v_lshlrev_b32_e32 v34, 16, v58
	v_and_b32_e32 v37, 0xffff0000, v59
	v_and_b32_e32 v36, 0xffff0000, v58
	v_lshlrev_b32_e32 v43, 16, v57
	v_lshlrev_b32_e32 v42, 16, v56
	v_and_b32_e32 v49, 0xffff0000, v61
	v_and_b32_e32 v48, 0xffff0000, v60
	v_pk_mul_f32 v[46:47], v[0:1], v[46:47] op_sel_hi:[0,1]
	v_mov_b32_e32 v50, v66
	v_mov_b32_e32 v51, v68
	v_lshlrev_b32_e32 v23, 16, v55
	v_lshlrev_b32_e32 v22, 16, v54
	v_and_b32_e32 v25, 0xffff0000, v55
	v_and_b32_e32 v24, 0xffff0000, v54
	v_pk_mul_f32 v[34:35], v[0:1], v[34:35] op_sel_hi:[0,1]
	v_mov_b32_e32 v38, v70
	v_mov_b32_e32 v39, v72
	v_pk_mul_f32 v[36:37], v[0:1], v[36:37] op_sel_hi:[0,1]
	v_mov_b32_e32 v72, v71
	v_and_b32_e32 v45, 0xffff0000, v57
	v_and_b32_e32 v44, 0xffff0000, v56
	v_pk_mul_f32 v[46:47], v[50:51], v[46:47]
	v_pk_mul_f32 v[42:43], v[0:1], v[42:43] op_sel_hi:[0,1]
	v_mov_b32_e32 v50, v2
	v_mov_b32_e32 v51, v4
	v_pk_mul_f32 v[48:49], v[0:1], v[48:49] op_sel_hi:[0,1]
	v_mov_b32_e32 v68, v67
	v_pk_mul_f32 v[34:35], v[38:39], v[34:35]
	v_pk_mul_f32 v[22:23], v[0:1], v[22:23] op_sel_hi:[0,1]
	v_mov_b32_e32 v38, v62
	v_mov_b32_e32 v39, v64
	v_pk_mul_f32 v[36:37], v[72:73], v[36:37]
	v_pk_mul_f32 v[24:25], v[0:1], v[24:25] op_sel_hi:[0,1]
	v_mov_b32_e32 v64, v63
	v_pk_mul_f32 v[42:43], v[50:51], v[42:43]
	v_pk_mul_f32 v[48:49], v[68:69], v[48:49]
	v_pk_mul_f32 v[44:45], v[0:1], v[44:45] op_sel_hi:[0,1]
	v_mov_b32_e32 v4, v3
	v_pk_mul_f32 v[22:23], v[38:39], v[22:23]
	v_pk_mul_f32 v[24:25], v[64:65], v[24:25]
	v_pk_mul_f32 v[44:45], v[4:5], v[44:45]
	s_waitcnt vmcnt(0)
; template <int D, int ROT0, int HALF, bool GAIN, bool KEEP = true>
; DI void chunk_nr(u16* p, const float* __restrict__ gain, const float* __restrict__ tab) {
;     ...
;     if (v >= V0 && v < V0 + 2 * NRV) {
;       if (v >= V0 + NRV) continue;
;       const f32x8 x1 = bf8_to_f32(RAWV(v));
;       const f32x8 x2 = bf8_to_f32(RAWV(v + NRV));
;       f32x8 g1, g2;
;       if (GAIN) { g1 = *(const f32x8*)(gain + v * 8); g2 = *(const f32x8*)(gain + (v + NRV) * 8); }
;       const f32x8 t0 = *(const f32x8*)(tab + 2 * (v - V0) * 8);
;       const f32x8 t1 = *(const f32x8*)(tab + 2 * (v - V0) * 8 + 8);
;       f32x8 o1, o2;
; #pragma unroll
;       for (int e = 0; e < 8; ++e) {
;         float y1 = x1[e], y2 = x2[e];
;         if (GAIN) { y1 = y1 * rstd * g1[e]; y2 = y2 * rstd * g2[e]; }
;         const float c = (e < 4) ? t0[2 * e] : t1[2 * (e - 4)];
;         const float sn = (e < 4) ? t0[2 * e + 1] : t1[2 * (e - 4) + 1];
;         o1[e] = y1 * c - y2 * sn;
;         o2[e] = y2 * c + y1 * sn;
;       }
;       *(u32x4*)(p + v * 8) = f32_to_bf8(o1);
;       *(u32x4*)(p + (v + NRV) * 8) = f32_to_bf8(o2);
	v_mov_b32_e32 v40, v8
	v_mov_b32_e32 v41, v12
	v_mov_b32_e32 v12, v9
	v_mov_b32_e32 v51, v18
	v_mov_b32_e32 v18, v15
	v_mov_b32_e32 v15, v20
	v_mov_b32_e32 v20, v17
	v_mov_b32_e32 v39, v10
	v_mov_b32_e32 v10, v7
	v_pk_mul_f32 v[8:9], v[12:13], v[36:37]
	v_mov_b32_e32 v50, v14
	v_mov_b32_e32 v14, v16
	v_pk_mul_f32 v[4:5], v[20:21], v[48:49]
	v_mov_b32_e32 v38, v6
	v_pk_mul_f32 v[6:7], v[10:11], v[34:35]
	v_pk_fma_f32 v[8:9], v[40:41], v[24:25], v[8:9] neg_lo:[0,0,1] neg_hi:[0,0,1]
	v_pk_mul_f32 v[2:3], v[18:19], v[46:47]
	v_pk_fma_f32 v[4:5], v[14:15], v[44:45], v[4:5] neg_lo:[0,0,1] neg_hi:[0,0,1]
	v_pk_fma_f32 v[6:7], v[38:39], v[22:23], v[6:7] neg_lo:[0,0,1] neg_hi:[0,0,1]
	v_pk_fma_f32 v[2:3], v[50:51], v[42:43], v[2:3] neg_lo:[0,0,1] neg_hi:[0,0,1]
	v_bfe_u32 v0, v5, 16, 1
	v_bfe_u32 v16, v4, 16, 1
	v_bfe_u32 v17, v9, 16, 1
	v_bfe_u32 v52, v8, 16, 1
	v_add3_u32 v8, v8, v52, s54
	v_add3_u32 v9, v9, v17, s54
	v_add3_u32 v4, v4, v16, s54
	v_add3_u32 v0, v5, v0, s54
	v_bfe_u32 v5, v6, 16, 1
	v_bfe_u32 v16, v7, 16, 1
	v_bfe_u32 v17, v2, 16, 1
	v_bfe_u32 v52, v3, 16, 1
	v_add3_u32 v3, v3, v52, s54
	v_add3_u32 v2, v2, v17, s54
	v_add3_u32 v7, v7, v16, s54
	v_add3_u32 v5, v6, v5, s54
	v_lshrrev_b32_e32 v6, 16, v5
	v_lshrrev_b32_e32 v7, 16, v7
	v_lshrrev_b32_e32 v2, 16, v2
	v_lshrrev_b32_e32 v3, 16, v3
	v_and_or_b32 v5, v0, s56, v3
	v_and_or_b32 v4, v4, s56, v2
	v_and_or_b32 v3, v9, s56, v7
	v_and_or_b32 v2, v8, s56, v6
	global_store_dwordx4 v[32:33], v[2:5], off offset:304
	v_pk_mul_f32 v[8:9], v[20:21], v[44:45]
	v_pk_mul_f32 v[6:7], v[18:19], v[42:43]
	v_pk_mul_f32 v[4:5], v[12:13], v[24:25]
	v_pk_mul_f32 v[2:3], v[10:11], v[22:23]
	v_pk_fma_f32 v[4:5], v[40:41], v[36:37], v[4:5]
	v_pk_fma_f32 v[8:9], v[14:15], v[48:49], v[8:9]
	v_pk_fma_f32 v[2:3], v[38:39], v[34:35], v[2:3]
	v_pk_fma_f32 v[6:7], v[50:51], v[46:47], v[6:7]
	v_bfe_u32 v0, v9, 16, 1
	v_bfe_u32 v10, v8, 16, 1
	v_bfe_u32 v11, v5, 16, 1
	v_bfe_u32 v12, v4, 16, 1
	v_add3_u32 v12, v4, v12, s54
	v_add3_u32 v11, v5, v11, s54
	v_add3_u32 v4, v8, v10, s54
	v_add3_u32 v0, v9, v0, s54
	v_bfe_u32 v5, v2, 16, 1
	v_bfe_u32 v8, v3, 16, 1
	v_bfe_u32 v9, v6, 16, 1
	v_bfe_u32 v10, v7, 16, 1
	v_add3_u32 v7, v7, v10, s54
	v_add3_u32 v6, v6, v9, s54
	v_add3_u32 v3, v3, v8, s54
	v_add3_u32 v2, v2, v5, s54
	v_lshrrev_b32_e32 v2, 16, v2
	v_lshrrev_b32_e32 v3, 16, v3
	v_lshrrev_b32_e32 v6, 16, v6
	v_lshrrev_b32_e32 v5, 16, v7
	v_and_or_b32 v5, v0, s56, v5
	v_and_or_b32 v4, v4, s56, v6
	v_and_or_b32 v3, v11, s56, v3
	v_and_or_b32 v2, v12, s56, v2
	global_store_dwordx4 v[32:33], v[2:5], off offset:368
	s_mov_b64 s[10:11], 0
